# pre-barrier MFMA count 8 in the merged 32-MFMA steps only (EpiF32 loop stays at 4)
# baseline (speedup 1.0000x reference)
; #define PG8_STAGE(bufoff, gbase, voff) do { _Pragma("unroll") for (int _i = 0; _i < 2; ++_i) \
;         __builtin_amdgcn_global_load_lds((const unsigned*)((const char*)(gbase) + (voff)[_i]), (LAS unsigned*)(lds + (bufoff) + ldsw + _i * 8192), 16, 0, 0); } while (0)
; #define PG8_LDA(dst, b, h) do { _Pragma("unroll") for (int m = 0; m < 4; ++m) _Pragma("unroll") for (int k = 0; k < 2; ++k) dst[m][k] = *(const LAS bf16x8*)(lds + PG8_SA(b, h) + aoff + m * 2048 + k * 1024); } while (0)
; #define PG8_LDB(dst, b, h) do { _Pragma("unroll") for (int n = 0; n < 2; ++n) _Pragma("unroll") for (int k = 0; k < 2; ++k) dst[n][k] = *(const LAS bf16x8*)(lds + PG8_SB(b, h) + boff + n * 2048 + k * 1024); } while (0)
; #define PG8_MMA(ai, bj, At, Bt) do { __builtin_amdgcn_s_setprio(1); _Pragma("unroll") for (int m = 0; m < 4; ++m) _Pragma("unroll") for (int n = 0; n < 2; ++n) _Pragma("unroll") for (int k = 0; k < 2; ++k) \
;         acc[ai][bj][m][n] = __builtin_amdgcn_mfma_f32_16x16x32_bf16(Bt[n][k], At[m][k], acc[ai][bj][m][n], 0, 0, 0); __builtin_amdgcn_s_setprio(0); } while (0)
; #define PG8_WAIT_V(n) asm volatile("s_waitcnt vmcnt(" #n ")" ::: "memory")
; #define PG8_WAIT_L(n) asm volatile("s_waitcnt lgkmcnt(" #n ")" ::: "memory")
; #define PG8_BAR __builtin_amdgcn_s_barrier()
; #define PG8_SCHED __builtin_amdgcn_sched_barrier(0)
; template <class Epi>
; __device__ __forceinline__ void gemm_phase(LAS unsigned char* lds, const Gemm g, const Sched& S, const Epi& E) {
;     ...
;             PG8_LDB(B0, 0, 0); PG8_SCHED; PG8_LDA(At, 0, 0); PG8_STAGE(PG8_SA(1, 1), a1 + hstepA, voffA);
;             PG8_WAIT_L(8); PG8_BAR; PG8_WAIT_L(0); PG8_MMA(0, 0, At, B0); PG8_BAR; PG8_SCHED;
;             PG8_LDB(B1, 0, 1); PG8_STAGE(PG8_SB(0, 0), b2, voffB);
;             PG8_BAR; PG8_WAIT_L(0); PG8_MMA(0, 1, At, B1); PG8_BAR;
;             PG8_LDA(At, 0, 1); PG8_STAGE(PG8_SA(0, 0), a2, voffA);
;             PG8_BAR; PG8_WAIT_L(0); PG8_MMA(1, 0, At, B0); PG8_BAR; PG8_SCHED;
;             PG8_STAGE(PG8_SB(0, 1), b2 + hstepB, voffB);
;             PG8_WAIT_V(6); PG8_BAR; PG8_MMA(1, 1, At, B1); PG8_BAR;
.Lresync_y_400:
.LBB0_400:
	s_add_i32 s14, s66, 2
	s_add_u32 s8, s92, 0x80
	s_addc_u32 s9, s93, 0
	s_add_i32 s15, 0, 0x10000
	v_add_u32_e32 v148, s15, v152
	ds_read_b128 v[144:147], v148
	ds_read_b128 v[172:175], v148 offset:1024
	ds_read_b128 v[176:179], v148 offset:2048
	ds_read_b128 v[180:183], v148 offset:3072
	s_cmp_eq_u32 s71, s66
	s_cselect_b32 s95, s55, s9
	s_cselect_b32 s94, s57, s8
	s_cselect_b32 s97, s59, s35
	s_cselect_b32 s96, s65, s34
	v_lshl_add_u64 v[148:149], s[92:93], 0, v[138:139]
	s_add_i32 m0, s42, 0xc000
	ds_read_b128 v[184:187], v171
	ds_read_b128 v[188:191], v171 offset:1024
	ds_read_b128 v[196:199], v171 offset:2048
	ds_read_b128 v[200:203], v171 offset:3072
	ds_read_b128 v[204:207], v171 offset:4096
	ds_read_b128 v[208:211], v171 offset:5120
	ds_read_b128 v[212:215], v171 offset:6144
	ds_read_b128 v[222:225], v171 offset:7168
	global_load_lds_dwordx4 v[148:149], off
	v_lshl_add_u64 v[148:149], s[92:93], 0, v[140:141]
	s_add_i32 m0, s42, 0xe000
	s_nop 0
	global_load_lds_dwordx4 v[148:149], off
	s_add_i32 s8, 0, 0x14000
	v_add_u32_e32 v148, s8, v152
	ds_read_b128 v[226:229], v148
	ds_read_b128 v[230:233], v148 offset:1024
	ds_read_b128 v[234:237], v148 offset:2048
	ds_read_b128 v[238:241], v148 offset:3072
	s_waitcnt vmcnt(8)
	s_waitcnt lgkmcnt(0)
	v_mfma_f32_16x16x32_bf16 v[126:129], v[144:147], v[184:187], v[126:129]
	v_mfma_f32_16x16x32_bf16 v[122:125], v[176:179], v[184:187], v[122:125]
	v_mfma_f32_16x16x32_bf16 v[110:113], v[144:147], v[196:199], v[110:113]
	v_mfma_f32_16x16x32_bf16 v[106:109], v[176:179], v[196:199], v[106:109]
	v_mfma_f32_16x16x32_bf16 v[94:97], v[144:147], v[204:207], v[94:97]
	v_mfma_f32_16x16x32_bf16 v[90:93], v[176:179], v[204:207], v[90:93]
	v_mfma_f32_16x16x32_bf16 v[78:81], v[144:147], v[212:215], v[78:81]
	v_mfma_f32_16x16x32_bf16 v[74:77], v[176:179], v[212:215], v[74:77]
	s_barrier
	s_setprio 1
	v_mfma_f32_16x16x32_bf16 v[126:129], v[172:175], v[188:191], v[126:129]
	v_mfma_f32_16x16x32_bf16 v[122:125], v[180:183], v[188:191], v[122:125]
	v_mfma_f32_16x16x32_bf16 v[110:113], v[172:175], v[200:203], v[110:113]
	v_mfma_f32_16x16x32_bf16 v[106:109], v[180:183], v[200:203], v[106:109]
	v_mfma_f32_16x16x32_bf16 v[94:97], v[172:175], v[208:211], v[94:97]
	v_mfma_f32_16x16x32_bf16 v[90:93], v[180:183], v[208:211], v[90:93]
	v_mfma_f32_16x16x32_bf16 v[78:81], v[172:175], v[222:225], v[78:81]
	v_mfma_f32_16x16x32_bf16 v[74:77], v[180:183], v[222:225], v[74:77]
	v_mfma_f32_16x16x32_bf16 v[118:121], v[226:229], v[184:187], v[118:121]
	v_mfma_f32_16x16x32_bf16 v[114:117], v[234:237], v[184:187], v[114:117]
	v_mfma_f32_16x16x32_bf16 v[102:105], v[226:229], v[196:199], v[102:105]
	v_mfma_f32_16x16x32_bf16 v[98:101], v[234:237], v[196:199], v[98:101]
	v_mfma_f32_16x16x32_bf16 v[86:89], v[226:229], v[204:207], v[86:89]
	v_mfma_f32_16x16x32_bf16 v[82:85], v[234:237], v[204:207], v[82:85]
	v_mfma_f32_16x16x32_bf16 v[70:73], v[226:229], v[212:215], v[70:73]
	v_mfma_f32_16x16x32_bf16 v[66:69], v[234:237], v[212:215], v[66:69]
	v_mfma_f32_16x16x32_bf16 v[118:121], v[230:233], v[188:191], v[118:121]
	v_mfma_f32_16x16x32_bf16 v[114:117], v[238:241], v[188:191], v[114:117]
	v_mfma_f32_16x16x32_bf16 v[102:105], v[230:233], v[200:203], v[102:105]
	v_mfma_f32_16x16x32_bf16 v[98:101], v[238:241], v[200:203], v[98:101]
	v_mfma_f32_16x16x32_bf16 v[86:89], v[230:233], v[208:211], v[86:89]
	v_mfma_f32_16x16x32_bf16 v[82:85], v[238:241], v[208:211], v[82:85]
	v_mfma_f32_16x16x32_bf16 v[70:73], v[230:233], v[222:225], v[70:73]
	v_mfma_f32_16x16x32_bf16 v[66:69], v[238:241], v[222:225], v[66:69]
	s_setprio 0
	s_barrier
	s_add_i32 s9, s15, s39
	v_lshl_add_u64 v[148:149], s[96:97], 0, v[132:133]
	s_mov_b32 m0, s9
	v_lshl_add_u64 v[192:193], s[96:97], 0, v[136:137]
	global_load_lds_dwordx4 v[148:149], off
	s_add_i32 m0, s9, 0x2000
	s_nop 0
	global_load_lds_dwordx4 v[192:193], off
	s_mov_b32 m0, s42
	v_lshl_add_u64 v[194:195], s[94:95], 0, v[130:131]
	ds_read_b128 v[184:187], v171 offset:16384
	ds_read_b128 v[188:191], v171 offset:17408
	ds_read_b128 v[196:199], v171 offset:18432
	ds_read_b128 v[200:203], v171 offset:19456
	ds_read_b128 v[204:207], v171 offset:20480
	ds_read_b128 v[208:211], v171 offset:21504
	ds_read_b128 v[212:215], v171 offset:22528
	ds_read_b128 v[222:225], v171 offset:23552
	global_load_lds_dwordx4 v[194:195], off
	v_lshl_add_u64 v[216:217], s[94:95], 0, v[134:135]
	s_mov_b32 m0, s43
	s_nop 0
	global_load_lds_dwordx4 v[216:217], off
	s_add_u32 s96, s96, s78
	s_addc_u32 s97, s97, s79
	s_add_i32 s8, s8, s39
	v_lshl_add_u64 v[242:243], s[96:97], 0, v[132:133]
	s_mov_b32 m0, s8
	v_lshl_add_u64 v[244:245], s[96:97], 0, v[136:137]
	global_load_lds_dwordx4 v[242:243], off
	s_add_i32 m0, s8, 0x2000
	s_nop 0
	global_load_lds_dwordx4 v[244:245], off
	s_waitcnt vmcnt(8)
	s_waitcnt lgkmcnt(0)
	v_mfma_f32_16x16x32_bf16 v[62:65], v[144:147], v[184:187], v[62:65]
	v_mfma_f32_16x16x32_bf16 v[58:61], v[176:179], v[184:187], v[58:61]
	v_mfma_f32_16x16x32_bf16 v[50:53], v[144:147], v[196:199], v[50:53]
	v_mfma_f32_16x16x32_bf16 v[42:45], v[176:179], v[196:199], v[42:45]
	v_mfma_f32_16x16x32_bf16 v[34:37], v[144:147], v[204:207], v[34:37]
	v_mfma_f32_16x16x32_bf16 v[26:29], v[176:179], v[204:207], v[26:29]
	v_mfma_f32_16x16x32_bf16 v[18:21], v[144:147], v[212:215], v[18:21]
	v_mfma_f32_16x16x32_bf16 v[10:13], v[176:179], v[212:215], v[10:13]
	s_barrier
; #define PG8_STAGE(bufoff, gbase, voff) do { _Pragma("unroll") for (int _i = 0; _i < 2; ++_i) \
;         __builtin_amdgcn_global_load_lds((const unsigned*)((const char*)(gbase) + (voff)[_i]), (LAS unsigned*)(lds + (bufoff) + ldsw + _i * 8192), 16, 0, 0); } while (0)
; #define PG8_LDA(dst, b, h) do { _Pragma("unroll") for (int m = 0; m < 4; ++m) _Pragma("unroll") for (int k = 0; k < 2; ++k) dst[m][k] = *(const LAS bf16x8*)(lds + PG8_SA(b, h) + aoff + m * 2048 + k * 1024); } while (0)
; #define PG8_LDB(dst, b, h) do { _Pragma("unroll") for (int n = 0; n < 2; ++n) _Pragma("unroll") for (int k = 0; k < 2; ++k) dst[n][k] = *(const LAS bf16x8*)(lds + PG8_SB(b, h) + boff + n * 2048 + k * 1024); } while (0)
; #define PG8_MMA(ai, bj, At, Bt) do { __builtin_amdgcn_s_setprio(1); _Pragma("unroll") for (int m = 0; m < 4; ++m) _Pragma("unroll") for (int n = 0; n < 2; ++n) _Pragma("unroll") for (int k = 0; k < 2; ++k) \
;         acc[ai][bj][m][n] = __builtin_amdgcn_mfma_f32_16x16x32_bf16(Bt[n][k], At[m][k], acc[ai][bj][m][n], 0, 0, 0); __builtin_amdgcn_s_setprio(0); } while (0)
; #define PG8_WAIT_V(n) asm volatile("s_waitcnt vmcnt(" #n ")" ::: "memory")
; #define PG8_WAIT_L(n) asm volatile("s_waitcnt lgkmcnt(" #n ")" ::: "memory")
; #define PG8_BAR __builtin_amdgcn_s_barrier()
; #define PG8_SCHED __builtin_amdgcn_sched_barrier(0)
; template <class Epi>
; __device__ __forceinline__ void gemm_phase(LAS unsigned char* lds, const Gemm g, const Sched& S, const Epi& E) {
;     ...
;             PG8_WAIT_V(6); PG8_BAR; PG8_MMA(1, 1, At, B1); PG8_BAR;
;             PG8_LDB(B0, 1, 0); PG8_SCHED; PG8_LDA(At, 1, 0); PG8_STAGE(PG8_SA(0, 1), a2 + hstepA, voffA);
;             PG8_WAIT_L(8); PG8_BAR; PG8_WAIT_L(0); PG8_MMA(0, 0, At, B0); PG8_BAR; PG8_SCHED;
;             PG8_LDB(B1, 1, 1); PG8_STAGE(PG8_SB(1, 0), b3, voffB);
;             PG8_BAR; PG8_WAIT_L(0); PG8_MMA(0, 1, At, B1); PG8_BAR;
;             PG8_LDA(At, 1, 1); PG8_STAGE(PG8_SA(1, 0), a3, voffA);
;             PG8_BAR; PG8_WAIT_L(0); PG8_MMA(1, 0, At, B0); PG8_BAR; PG8_SCHED;
	s_setprio 1
	v_mfma_f32_16x16x32_bf16 v[62:65], v[172:175], v[188:191], v[62:65]
	v_mfma_f32_16x16x32_bf16 v[58:61], v[180:183], v[188:191], v[58:61]
	v_mfma_f32_16x16x32_bf16 v[50:53], v[172:175], v[200:203], v[50:53]
	v_mfma_f32_16x16x32_bf16 v[42:45], v[180:183], v[200:203], v[42:45]
	v_mfma_f32_16x16x32_bf16 v[34:37], v[172:175], v[208:211], v[34:37]
	v_mfma_f32_16x16x32_bf16 v[26:29], v[180:183], v[208:211], v[26:29]
	v_mfma_f32_16x16x32_bf16 v[18:21], v[172:175], v[222:225], v[18:21]
	v_mfma_f32_16x16x32_bf16 v[10:13], v[180:183], v[222:225], v[10:13]
	v_mfma_f32_16x16x32_bf16 v[54:57], v[226:229], v[184:187], v[54:57]
	v_mfma_f32_16x16x32_bf16 v[46:49], v[234:237], v[184:187], v[46:49]
	v_mfma_f32_16x16x32_bf16 v[38:41], v[226:229], v[196:199], v[38:41]
	v_mfma_f32_16x16x32_bf16 v[30:33], v[234:237], v[196:199], v[30:33]
	v_mfma_f32_16x16x32_bf16 v[22:25], v[226:229], v[204:207], v[22:25]
	v_mfma_f32_16x16x32_bf16 v[14:17], v[234:237], v[204:207], v[14:17]
	v_mfma_f32_16x16x32_bf16 v[6:9], v[226:229], v[212:215], v[6:9]
	v_mfma_f32_16x16x32_bf16 v[2:5], v[234:237], v[212:215], v[2:5]
	v_mfma_f32_16x16x32_bf16 v[54:57], v[230:233], v[188:191], v[54:57]
	v_mfma_f32_16x16x32_bf16 v[46:49], v[238:241], v[188:191], v[46:49]
	v_mfma_f32_16x16x32_bf16 v[38:41], v[230:233], v[200:203], v[38:41]
	v_mfma_f32_16x16x32_bf16 v[30:33], v[238:241], v[200:203], v[30:33]
	v_mfma_f32_16x16x32_bf16 v[22:25], v[230:233], v[208:211], v[22:25]
	v_mfma_f32_16x16x32_bf16 v[14:17], v[238:241], v[208:211], v[14:17]
	v_mfma_f32_16x16x32_bf16 v[6:9], v[230:233], v[222:225], v[6:9]
	v_mfma_f32_16x16x32_bf16 v[2:5], v[238:241], v[222:225], v[2:5]
	s_setprio 0
	s_barrier
	s_add_i32 s8, 0, 0x18000
	v_add_u32_e32 v180, s8, v152
	ds_read_b128 v[144:147], v180
	ds_read_b128 v[172:175], v180 offset:1024
	ds_read_b128 v[176:179], v180 offset:2048
	ds_read_b128 v[180:183], v180 offset:3072
	s_add_u32 s94, s94, s4
	s_addc_u32 s95, s95, s5
	s_mov_b32 m0, s52
	v_lshl_add_u64 v[226:227], s[94:95], 0, v[130:131]
	ds_read_b128 v[184:187], v171 offset:32768
	ds_read_b128 v[188:191], v171 offset:33792
	ds_read_b128 v[196:199], v171 offset:34816
	ds_read_b128 v[200:203], v171 offset:35840
	ds_read_b128 v[204:207], v171 offset:36864
	ds_read_b128 v[208:211], v171 offset:37888
	ds_read_b128 v[212:215], v171 offset:38912
	ds_read_b128 v[222:225], v171 offset:39936
	global_load_lds_dwordx4 v[226:227], off
	v_lshl_add_u64 v[226:227], s[94:95], 0, v[134:135]
	s_mov_b32 m0, s53
	s_nop 0
	global_load_lds_dwordx4 v[226:227], off
	s_add_i32 s9, 0, 0x1c000
	v_add_u32_e32 v218, s9, v152
	ds_read_b128 v[226:229], v218
	ds_read_b128 v[230:233], v218 offset:1024
	ds_read_b128 v[234:237], v218 offset:2048
	ds_read_b128 v[238:241], v218 offset:3072
	s_waitcnt vmcnt(8)
	s_waitcnt lgkmcnt(0)
	v_mfma_f32_16x16x32_bf16 v[126:129], v[144:147], v[184:187], v[126:129]
	v_mfma_f32_16x16x32_bf16 v[122:125], v[176:179], v[184:187], v[122:125]
	v_mfma_f32_16x16x32_bf16 v[110:113], v[144:147], v[196:199], v[110:113]
	v_mfma_f32_16x16x32_bf16 v[106:109], v[176:179], v[196:199], v[106:109]
	v_mfma_f32_16x16x32_bf16 v[94:97], v[144:147], v[204:207], v[94:97]
	v_mfma_f32_16x16x32_bf16 v[90:93], v[176:179], v[204:207], v[90:93]
	v_mfma_f32_16x16x32_bf16 v[78:81], v[144:147], v[212:215], v[78:81]
	v_mfma_f32_16x16x32_bf16 v[74:77], v[176:179], v[212:215], v[74:77]
	s_barrier
	s_setprio 1
	v_mfma_f32_16x16x32_bf16 v[126:129], v[172:175], v[188:191], v[126:129]
	v_mfma_f32_16x16x32_bf16 v[122:125], v[180:183], v[188:191], v[122:125]
	v_mfma_f32_16x16x32_bf16 v[110:113], v[172:175], v[200:203], v[110:113]
	v_mfma_f32_16x16x32_bf16 v[106:109], v[180:183], v[200:203], v[106:109]
	v_mfma_f32_16x16x32_bf16 v[94:97], v[172:175], v[208:211], v[94:97]
	v_mfma_f32_16x16x32_bf16 v[90:93], v[180:183], v[208:211], v[90:93]
	v_mfma_f32_16x16x32_bf16 v[78:81], v[172:175], v[222:225], v[78:81]
	v_mfma_f32_16x16x32_bf16 v[74:77], v[180:183], v[222:225], v[74:77]
	v_mfma_f32_16x16x32_bf16 v[118:121], v[226:229], v[184:187], v[118:121]
	v_mfma_f32_16x16x32_bf16 v[114:117], v[234:237], v[184:187], v[114:117]
	v_mfma_f32_16x16x32_bf16 v[102:105], v[226:229], v[196:199], v[102:105]
	v_mfma_f32_16x16x32_bf16 v[98:101], v[234:237], v[196:199], v[98:101]
	v_mfma_f32_16x16x32_bf16 v[86:89], v[226:229], v[204:207], v[86:89]
	v_mfma_f32_16x16x32_bf16 v[82:85], v[234:237], v[204:207], v[82:85]
	v_mfma_f32_16x16x32_bf16 v[70:73], v[226:229], v[212:215], v[70:73]
	v_mfma_f32_16x16x32_bf16 v[66:69], v[234:237], v[212:215], v[66:69]
	v_mfma_f32_16x16x32_bf16 v[118:121], v[230:233], v[188:191], v[118:121]
	v_mfma_f32_16x16x32_bf16 v[114:117], v[238:241], v[188:191], v[114:117]
	v_mfma_f32_16x16x32_bf16 v[102:105], v[230:233], v[200:203], v[102:105]
	v_mfma_f32_16x16x32_bf16 v[98:101], v[238:241], v[200:203], v[98:101]
	v_mfma_f32_16x16x32_bf16 v[86:89], v[230:233], v[208:211], v[86:89]
	v_mfma_f32_16x16x32_bf16 v[82:85], v[238:241], v[208:211], v[82:85]
	v_mfma_f32_16x16x32_bf16 v[70:73], v[230:233], v[222:225], v[70:73]
	v_mfma_f32_16x16x32_bf16 v[66:69], v[238:241], v[222:225], v[66:69]
	s_setprio 0
	s_barrier
; #define PG8_STAGE(bufoff, gbase, voff) do { _Pragma("unroll") for (int _i = 0; _i < 2; ++_i) \
;         __builtin_amdgcn_global_load_lds((const unsigned*)((const char*)(gbase) + (voff)[_i]), (LAS unsigned*)(lds + (bufoff) + ldsw + _i * 8192), 16, 0, 0); } while (0)
; #define PG8_LDA(dst, b, h) do { _Pragma("unroll") for (int m = 0; m < 4; ++m) _Pragma("unroll") for (int k = 0; k < 2; ++k) dst[m][k] = *(const LAS bf16x8*)(lds + PG8_SA(b, h) + aoff + m * 2048 + k * 1024); } while (0)
; #define PG8_MMA(ai, bj, At, Bt) do { __builtin_amdgcn_s_setprio(1); _Pragma("unroll") for (int m = 0; m < 4; ++m) _Pragma("unroll") for (int n = 0; n < 2; ++n) _Pragma("unroll") for (int k = 0; k < 2; ++k) \
;         acc[ai][bj][m][n] = __builtin_amdgcn_mfma_f32_16x16x32_bf16(Bt[n][k], At[m][k], acc[ai][bj][m][n], 0, 0, 0); __builtin_amdgcn_s_setprio(0); } while (0)
; #define PG8_WAIT_V(n) asm volatile("s_waitcnt vmcnt(" #n ")" ::: "memory")
; #define PG8_WAIT_L(n) asm volatile("s_waitcnt lgkmcnt(" #n ")" ::: "memory")
; #define PG8_BAR __builtin_amdgcn_s_barrier()
; #define PG8_SCHED __builtin_amdgcn_sched_barrier(0)
; template <class Epi>
; __device__ __forceinline__ void gemm_phase(LAS unsigned char* lds, const Gemm g, const Sched& S, const Epi& E) {
;     ...
;             PG8_LDA(At, 1, 1); PG8_STAGE(PG8_SA(1, 0), a3, voffA);
;             PG8_BAR; PG8_WAIT_L(0); PG8_MMA(1, 0, At, B0); PG8_BAR; PG8_SCHED;
;             PG8_STAGE(PG8_SB(1, 1), b3 + hstepB, voffB);
;             PG8_WAIT_V(6); PG8_BAR; PG8_MMA(1, 1, At, B1); PG8_BAR;
;         }
	s_add_i32 s8, s8, s39
	v_lshl_add_u64 v[148:149], v[148:149], 0, s[60:61]
	s_mov_b32 m0, s8
	s_nop 0
	global_load_lds_dwordx4 v[148:149], off
	v_lshl_add_u64 v[148:149], v[192:193], 0, s[60:61]
	s_add_i32 m0, s8, 0x2000
	s_nop 0
	global_load_lds_dwordx4 v[148:149], off
	s_mov_b32 m0, s67
	v_lshl_add_u64 v[148:149], v[194:195], 0, s[60:61]
	ds_read_b128 v[184:187], v171 offset:49152
	ds_read_b128 v[188:191], v171 offset:50176
	ds_read_b128 v[196:199], v171 offset:51200
	ds_read_b128 v[200:203], v171 offset:52224
	ds_read_b128 v[204:207], v171 offset:53248
	ds_read_b128 v[208:211], v171 offset:54272
	ds_read_b128 v[212:215], v171 offset:55296
	ds_read_b128 v[222:225], v171 offset:56320
	global_load_lds_dwordx4 v[148:149], off
	v_lshl_add_u64 v[148:149], v[216:217], 0, s[60:61]
	s_mov_b32 m0, s2
	s_nop 0
	global_load_lds_dwordx4 v[148:149], off
	s_add_i32 s8, s9, s39
	v_lshl_add_u64 v[148:149], v[242:243], 0, s[60:61]
	s_mov_b32 m0, s8
	s_nop 0
	global_load_lds_dwordx4 v[148:149], off
	v_lshl_add_u64 v[148:149], v[244:245], 0, s[60:61]
	s_add_i32 m0, s8, 0x2000
	s_nop 0
	global_load_lds_dwordx4 v[148:149], off
	s_waitcnt vmcnt(8)
	s_waitcnt lgkmcnt(0)
	v_mfma_f32_16x16x32_bf16 v[62:65], v[144:147], v[184:187], v[62:65]
	v_mfma_f32_16x16x32_bf16 v[58:61], v[176:179], v[184:187], v[58:61]
	v_mfma_f32_16x16x32_bf16 v[50:53], v[144:147], v[196:199], v[50:53]
	v_mfma_f32_16x16x32_bf16 v[42:45], v[176:179], v[196:199], v[42:45]
	v_mfma_f32_16x16x32_bf16 v[34:37], v[144:147], v[204:207], v[34:37]
	v_mfma_f32_16x16x32_bf16 v[26:29], v[176:179], v[204:207], v[26:29]
	v_mfma_f32_16x16x32_bf16 v[18:21], v[144:147], v[212:215], v[18:21]
	v_mfma_f32_16x16x32_bf16 v[10:13], v[176:179], v[212:215], v[10:13]
	s_barrier
	s_setprio 1
	v_mfma_f32_16x16x32_bf16 v[62:65], v[172:175], v[188:191], v[62:65]
	v_mfma_f32_16x16x32_bf16 v[58:61], v[180:183], v[188:191], v[58:61]
	v_mfma_f32_16x16x32_bf16 v[50:53], v[172:175], v[200:203], v[50:53]
	v_mfma_f32_16x16x32_bf16 v[42:45], v[180:183], v[200:203], v[42:45]
	v_mfma_f32_16x16x32_bf16 v[34:37], v[172:175], v[208:211], v[34:37]
	v_mfma_f32_16x16x32_bf16 v[26:29], v[180:183], v[208:211], v[26:29]
	v_mfma_f32_16x16x32_bf16 v[18:21], v[172:175], v[222:225], v[18:21]
	v_mfma_f32_16x16x32_bf16 v[10:13], v[180:183], v[222:225], v[10:13]
	v_mfma_f32_16x16x32_bf16 v[54:57], v[226:229], v[184:187], v[54:57]
	v_mfma_f32_16x16x32_bf16 v[46:49], v[234:237], v[184:187], v[46:49]
	v_mfma_f32_16x16x32_bf16 v[38:41], v[226:229], v[196:199], v[38:41]
	v_mfma_f32_16x16x32_bf16 v[30:33], v[234:237], v[196:199], v[30:33]
	v_mfma_f32_16x16x32_bf16 v[22:25], v[226:229], v[204:207], v[22:25]
	v_mfma_f32_16x16x32_bf16 v[14:17], v[234:237], v[204:207], v[14:17]
	v_mfma_f32_16x16x32_bf16 v[6:9], v[226:229], v[212:215], v[6:9]
	v_mfma_f32_16x16x32_bf16 v[2:5], v[234:237], v[212:215], v[2:5]
	v_mfma_f32_16x16x32_bf16 v[54:57], v[230:233], v[188:191], v[54:57]
	v_mfma_f32_16x16x32_bf16 v[46:49], v[238:241], v[188:191], v[46:49]
	v_mfma_f32_16x16x32_bf16 v[38:41], v[230:233], v[200:203], v[38:41]
	v_mfma_f32_16x16x32_bf16 v[30:33], v[238:241], v[200:203], v[30:33]
	v_mfma_f32_16x16x32_bf16 v[22:25], v[230:233], v[208:211], v[22:25]
	v_mfma_f32_16x16x32_bf16 v[14:17], v[238:241], v[208:211], v[14:17]
	v_mfma_f32_16x16x32_bf16 v[6:9], v[230:233], v[222:225], v[6:9]
	v_mfma_f32_16x16x32_bf16 v[2:5], v[238:241], v[222:225], v[2:5]
	s_setprio 0
	s_add_u32 s92, s92, 0x100
	s_addc_u32 s93, s93, 0
	s_add_u32 s34, s34, 0x100
	s_addc_u32 s35, s35, 0
	s_cmp_ge_u32 s14, s73
	s_mov_b32 s66, s14
	s_barrier
	s_cbranch_scc0 .LBB0_400
	v_readfirstlane_b32 s98, v219
	s_nop 1
	s_bitcmp1_b32 s98, 8
	s_cbranch_scc1 .Lresync_x_400
	s_barrier

; #define PG8_STAGE(bufoff, gbase, voff) do { _Pragma("unroll") for (int _i = 0; _i < 2; ++_i) \
;         __builtin_amdgcn_global_load_lds((const unsigned*)((const char*)(gbase) + (voff)[_i]), (LAS unsigned*)(lds + (bufoff) + ldsw + _i * 8192), 16, 0, 0); } while (0)
; #define PG8_LDA(dst, b, h) do { _Pragma("unroll") for (int m = 0; m < 4; ++m) _Pragma("unroll") for (int k = 0; k < 2; ++k) dst[m][k] = *(const LAS bf16x8*)(lds + PG8_SA(b, h) + aoff + m * 2048 + k * 1024); } while (0)
; #define PG8_LDB(dst, b, h) do { _Pragma("unroll") for (int n = 0; n < 2; ++n) _Pragma("unroll") for (int k = 0; k < 2; ++k) dst[n][k] = *(const LAS bf16x8*)(lds + PG8_SB(b, h) + boff + n * 2048 + k * 1024); } while (0)
; #define PG8_MMA(ai, bj, At, Bt) do { __builtin_amdgcn_s_setprio(1); _Pragma("unroll") for (int m = 0; m < 4; ++m) _Pragma("unroll") for (int n = 0; n < 2; ++n) _Pragma("unroll") for (int k = 0; k < 2; ++k) \
;         acc[ai][bj][m][n] = __builtin_amdgcn_mfma_f32_16x16x32_bf16(Bt[n][k], At[m][k], acc[ai][bj][m][n], 0, 0, 0); __builtin_amdgcn_s_setprio(0); } while (0)
; #define PG8_WAIT_V(n) asm volatile("s_waitcnt vmcnt(" #n ")" ::: "memory")
; #define PG8_WAIT_L(n) asm volatile("s_waitcnt lgkmcnt(" #n ")" ::: "memory")
; #define PG8_BAR __builtin_amdgcn_s_barrier()
; #define PG8_SCHED __builtin_amdgcn_sched_barrier(0)
; template <class Epi>
; __device__ __forceinline__ void gemm_phase(LAS unsigned char* lds, const Gemm g, const Sched& S, const Epi& E) {
;     ...
;             PG8_LDB(B0, 0, 0); PG8_SCHED; PG8_LDA(At, 0, 0); PG8_STAGE(PG8_SA(1, 1), a1 + hstepA, voffA);
;             PG8_WAIT_L(8); PG8_BAR; PG8_WAIT_L(0); PG8_MMA(0, 0, At, B0); PG8_BAR; PG8_SCHED;
;             PG8_LDB(B1, 0, 1); PG8_STAGE(PG8_SB(0, 0), b2, voffB);
;             PG8_BAR; PG8_WAIT_L(0); PG8_MMA(0, 1, At, B1); PG8_BAR;
;             PG8_LDA(At, 0, 1); PG8_STAGE(PG8_SA(0, 0), a2, voffA);
;             PG8_BAR; PG8_WAIT_L(0); PG8_MMA(1, 0, At, B0); PG8_BAR; PG8_SCHED;
;             PG8_STAGE(PG8_SB(0, 1), b2 + hstepB, voffB);
;             PG8_WAIT_V(6); PG8_BAR; PG8_MMA(1, 1, At, B1); PG8_BAR;
.Lresync_y_461:
.LBB0_461:
	s_add_i32 s14, s88, 2
	s_add_u32 s8, s4, 0x80
	s_addc_u32 s9, s5, 0
	s_add_i32 s15, 0, 0x10000
	v_add_u32_e32 v114, s15, v211
	ds_read_b128 v[82:85], v114
	ds_read_b128 v[94:97], v114 offset:1024
	ds_read_b128 v[98:101], v114 offset:2048
	ds_read_b128 v[114:117], v114 offset:3072
	s_cmp_eq_u32 s42, s88
	s_cselect_b32 s88, s57, s8
	s_cselect_b32 s89, s71, s9
	s_cselect_b32 s91, s59, s35
	s_cselect_b32 s90, s72, s34
	v_lshl_add_u64 v[178:179], s[4:5], 0, v[202:203]
	s_add_i32 m0, s24, 0xc000
	ds_read_b128 v[122:125], v213
	ds_read_b128 v[130:133], v213 offset:1024
	ds_read_b128 v[146:149], v213 offset:2048
	ds_read_b128 v[150:153], v213 offset:3072
	ds_read_b128 v[162:165], v213 offset:4096
	ds_read_b128 v[166:169], v213 offset:5120
	ds_read_b128 v[170:173], v213 offset:6144
	ds_read_b128 v[174:177], v213 offset:7168
	global_load_lds_dwordx4 v[178:179], off
	v_lshl_add_u64 v[178:179], s[4:5], 0, v[204:205]
	s_add_i32 m0, s24, 0xe000
	s_nop 0
	global_load_lds_dwordx4 v[178:179], off
	s_add_i32 s8, 0, 0x14000
	v_add_u32_e32 v190, s8, v211
	ds_read_b128 v[178:181], v190
	ds_read_b128 v[182:185], v190 offset:1024
	ds_read_b128 v[186:189], v190 offset:2048
	ds_read_b128 v[190:193], v190 offset:3072
	s_waitcnt vmcnt(8)
	s_waitcnt lgkmcnt(0)
	v_mfma_f32_16x16x32_bf16 v[158:161], v[82:85], v[122:125], v[158:161]
	v_mfma_f32_16x16x32_bf16 v[154:157], v[98:101], v[122:125], v[154:157]
	v_mfma_f32_16x16x32_bf16 v[134:137], v[82:85], v[146:149], v[134:137]
	v_mfma_f32_16x16x32_bf16 v[126:129], v[98:101], v[146:149], v[126:129]
	v_mfma_f32_16x16x32_bf16 v[106:109], v[82:85], v[162:165], v[106:109]
	v_mfma_f32_16x16x32_bf16 v[102:105], v[98:101], v[162:165], v[102:105]
	v_mfma_f32_16x16x32_bf16 v[78:81], v[82:85], v[170:173], v[78:81]
	v_mfma_f32_16x16x32_bf16 v[74:77], v[98:101], v[170:173], v[74:77]
	s_barrier
	s_setprio 1
	v_mfma_f32_16x16x32_bf16 v[158:161], v[94:97], v[130:133], v[158:161]
	v_mfma_f32_16x16x32_bf16 v[154:157], v[114:117], v[130:133], v[154:157]
	v_mfma_f32_16x16x32_bf16 v[134:137], v[94:97], v[150:153], v[134:137]
	v_mfma_f32_16x16x32_bf16 v[126:129], v[114:117], v[150:153], v[126:129]
	v_mfma_f32_16x16x32_bf16 v[106:109], v[94:97], v[166:169], v[106:109]
	v_mfma_f32_16x16x32_bf16 v[102:105], v[114:117], v[166:169], v[102:105]
	v_mfma_f32_16x16x32_bf16 v[78:81], v[94:97], v[174:177], v[78:81]
	v_mfma_f32_16x16x32_bf16 v[74:77], v[114:117], v[174:177], v[74:77]
	v_mfma_f32_16x16x32_bf16 v[142:145], v[178:181], v[122:125], v[142:145]
	v_mfma_f32_16x16x32_bf16 v[118:121], v[178:181], v[146:149], v[118:121]
	v_mfma_f32_16x16x32_bf16 v[110:113], v[186:189], v[146:149], v[110:113]
	v_mfma_f32_16x16x32_bf16 v[90:93], v[178:181], v[162:165], v[90:93]
	v_mfma_f32_16x16x32_bf16 v[86:89], v[186:189], v[162:165], v[86:89]
	v_mfma_f32_16x16x32_bf16 v[70:73], v[178:181], v[170:173], v[70:73]
	v_mfma_f32_16x16x32_bf16 v[66:69], v[186:189], v[170:173], v[66:69]
	v_mfma_f32_16x16x32_bf16 v[142:145], v[182:185], v[130:133], v[142:145]
	v_mfma_f32_16x16x32_bf16 v[122:125], v[186:189], v[122:125], v[138:141]
	v_mfma_f32_16x16x32_bf16 v[118:121], v[182:185], v[150:153], v[118:121]
	v_mfma_f32_16x16x32_bf16 v[110:113], v[190:193], v[150:153], v[110:113]
	v_mfma_f32_16x16x32_bf16 v[90:93], v[182:185], v[166:169], v[90:93]
	v_mfma_f32_16x16x32_bf16 v[86:89], v[190:193], v[166:169], v[86:89]
	v_mfma_f32_16x16x32_bf16 v[70:73], v[182:185], v[174:177], v[70:73]
	v_mfma_f32_16x16x32_bf16 v[66:69], v[190:193], v[174:177], v[66:69]
	v_mfma_f32_16x16x32_bf16 v[122:125], v[190:193], v[130:133], v[122:125]
	s_setprio 0
	s_barrier
	s_add_i32 s9, s15, s3
	v_lshl_add_u64 v[194:195], s[90:91], 0, v[0:1]
	s_mov_b32 m0, s9
	s_nop 0
	global_load_lds_dwordx4 v[194:195], off
	v_lshl_add_u64 v[206:207], s[90:91], 0, v[200:201]
	s_add_i32 m0, s9, 0x2000
	s_nop 0
	global_load_lds_dwordx4 v[206:207], off
	s_mov_b32 m0, s24
	v_lshl_add_u64 v[208:209], s[88:89], 0, v[196:197]
	ds_read_b128 v[130:133], v213 offset:16384
	ds_read_b128 v[138:141], v213 offset:17408
	ds_read_b128 v[146:149], v213 offset:18432
	ds_read_b128 v[150:153], v213 offset:19456
	ds_read_b128 v[162:165], v213 offset:20480
	ds_read_b128 v[166:169], v213 offset:21504
	ds_read_b128 v[170:173], v213 offset:22528
	ds_read_b128 v[174:177], v213 offset:23552
	global_load_lds_dwordx4 v[208:209], off
	v_lshl_add_u64 v[214:215], s[88:89], 0, v[198:199]
	s_mov_b32 m0, s33
	s_nop 0
	global_load_lds_dwordx4 v[214:215], off
	s_add_u32 s90, s90, s78
	s_addc_u32 s91, s91, s79
	s_add_i32 s8, s8, s3
	v_lshl_add_u64 v[216:217], s[90:91], 0, v[0:1]
	s_mov_b32 m0, s8
	v_lshl_add_u64 v[222:223], s[90:91], 0, v[200:201]
	global_load_lds_dwordx4 v[216:217], off
	s_add_i32 m0, s8, 0x2000
	s_nop 0
	global_load_lds_dwordx4 v[222:223], off
	s_waitcnt vmcnt(8)
	s_waitcnt lgkmcnt(0)
	v_mfma_f32_16x16x32_bf16 v[62:65], v[82:85], v[130:133], v[62:65]
	v_mfma_f32_16x16x32_bf16 v[58:61], v[98:101], v[130:133], v[58:61]
	v_mfma_f32_16x16x32_bf16 v[46:49], v[82:85], v[146:149], v[46:49]
	v_mfma_f32_16x16x32_bf16 v[42:45], v[98:101], v[146:149], v[42:45]
	v_mfma_f32_16x16x32_bf16 v[30:33], v[82:85], v[162:165], v[30:33]
	v_mfma_f32_16x16x32_bf16 v[26:29], v[98:101], v[162:165], v[26:29]
	v_mfma_f32_16x16x32_bf16 v[14:17], v[82:85], v[170:173], v[14:17]
	v_mfma_f32_16x16x32_bf16 v[10:13], v[98:101], v[170:173], v[10:13]
	s_barrier
; #define PG8_STAGE(bufoff, gbase, voff) do { _Pragma("unroll") for (int _i = 0; _i < 2; ++_i) \
;         __builtin_amdgcn_global_load_lds((const unsigned*)((const char*)(gbase) + (voff)[_i]), (LAS unsigned*)(lds + (bufoff) + ldsw + _i * 8192), 16, 0, 0); } while (0)
; #define PG8_LDA(dst, b, h) do { _Pragma("unroll") for (int m = 0; m < 4; ++m) _Pragma("unroll") for (int k = 0; k < 2; ++k) dst[m][k] = *(const LAS bf16x8*)(lds + PG8_SA(b, h) + aoff + m * 2048 + k * 1024); } while (0)
; #define PG8_LDB(dst, b, h) do { _Pragma("unroll") for (int n = 0; n < 2; ++n) _Pragma("unroll") for (int k = 0; k < 2; ++k) dst[n][k] = *(const LAS bf16x8*)(lds + PG8_SB(b, h) + boff + n * 2048 + k * 1024); } while (0)
; #define PG8_MMA(ai, bj, At, Bt) do { __builtin_amdgcn_s_setprio(1); _Pragma("unroll") for (int m = 0; m < 4; ++m) _Pragma("unroll") for (int n = 0; n < 2; ++n) _Pragma("unroll") for (int k = 0; k < 2; ++k) \
;         acc[ai][bj][m][n] = __builtin_amdgcn_mfma_f32_16x16x32_bf16(Bt[n][k], At[m][k], acc[ai][bj][m][n], 0, 0, 0); __builtin_amdgcn_s_setprio(0); } while (0)
; #define PG8_WAIT_V(n) asm volatile("s_waitcnt vmcnt(" #n ")" ::: "memory")
; #define PG8_WAIT_L(n) asm volatile("s_waitcnt lgkmcnt(" #n ")" ::: "memory")
; #define PG8_BAR __builtin_amdgcn_s_barrier()
; #define PG8_SCHED __builtin_amdgcn_sched_barrier(0)
; template <class Epi>
; __device__ __forceinline__ void gemm_phase(LAS unsigned char* lds, const Gemm g, const Sched& S, const Epi& E) {
;     ...
;             PG8_WAIT_V(6); PG8_BAR; PG8_MMA(1, 1, At, B1); PG8_BAR;
;             PG8_LDB(B0, 1, 0); PG8_SCHED; PG8_LDA(At, 1, 0); PG8_STAGE(PG8_SA(0, 1), a2 + hstepA, voffA);
;             PG8_WAIT_L(8); PG8_BAR; PG8_WAIT_L(0); PG8_MMA(0, 0, At, B0); PG8_BAR; PG8_SCHED;
;             PG8_LDB(B1, 1, 1); PG8_STAGE(PG8_SB(1, 0), b3, voffB);
;             PG8_BAR; PG8_WAIT_L(0); PG8_MMA(0, 1, At, B1); PG8_BAR;
;             PG8_LDA(At, 1, 1); PG8_STAGE(PG8_SA(1, 0), a3, voffA);
;             PG8_BAR; PG8_WAIT_L(0); PG8_MMA(1, 0, At, B0); PG8_BAR; PG8_SCHED;
	s_setprio 1
	v_mfma_f32_16x16x32_bf16 v[62:65], v[94:97], v[138:141], v[62:65]
	v_mfma_f32_16x16x32_bf16 v[58:61], v[114:117], v[138:141], v[58:61]
	v_mfma_f32_16x16x32_bf16 v[46:49], v[94:97], v[150:153], v[46:49]
	v_mfma_f32_16x16x32_bf16 v[42:45], v[114:117], v[150:153], v[42:45]
	v_mfma_f32_16x16x32_bf16 v[30:33], v[94:97], v[166:169], v[30:33]
	v_mfma_f32_16x16x32_bf16 v[26:29], v[114:117], v[166:169], v[26:29]
	v_mfma_f32_16x16x32_bf16 v[14:17], v[94:97], v[174:177], v[14:17]
	v_mfma_f32_16x16x32_bf16 v[10:13], v[114:117], v[174:177], v[10:13]
	v_mfma_f32_16x16x32_bf16 v[54:57], v[178:181], v[130:133], v[54:57]
	v_mfma_f32_16x16x32_bf16 v[50:53], v[186:189], v[130:133], v[50:53]
	v_mfma_f32_16x16x32_bf16 v[38:41], v[178:181], v[146:149], v[38:41]
	v_mfma_f32_16x16x32_bf16 v[34:37], v[186:189], v[146:149], v[34:37]
	v_mfma_f32_16x16x32_bf16 v[22:25], v[178:181], v[162:165], v[22:25]
	v_mfma_f32_16x16x32_bf16 v[18:21], v[186:189], v[162:165], v[18:21]
	v_mfma_f32_16x16x32_bf16 v[6:9], v[178:181], v[170:173], v[6:9]
	v_mfma_f32_16x16x32_bf16 v[2:5], v[186:189], v[170:173], v[2:5]
	v_mfma_f32_16x16x32_bf16 v[54:57], v[182:185], v[138:141], v[54:57]
	v_mfma_f32_16x16x32_bf16 v[50:53], v[190:193], v[138:141], v[50:53]
	v_mfma_f32_16x16x32_bf16 v[38:41], v[182:185], v[150:153], v[38:41]
	v_mfma_f32_16x16x32_bf16 v[34:37], v[190:193], v[150:153], v[34:37]
	v_mfma_f32_16x16x32_bf16 v[22:25], v[182:185], v[166:169], v[22:25]
	v_mfma_f32_16x16x32_bf16 v[18:21], v[190:193], v[166:169], v[18:21]
	v_mfma_f32_16x16x32_bf16 v[6:9], v[182:185], v[174:177], v[6:9]
	v_mfma_f32_16x16x32_bf16 v[2:5], v[190:193], v[174:177], v[2:5]
	s_setprio 0
	s_barrier
	s_add_i32 s8, 0, 0x18000
	v_add_u32_e32 v114, s8, v211
	ds_read_b128 v[82:85], v114
	ds_read_b128 v[94:97], v114 offset:1024
	ds_read_b128 v[98:101], v114 offset:2048
	ds_read_b128 v[114:117], v114 offset:3072
	s_add_u32 s88, s88, s36
	s_addc_u32 s89, s89, s37
	s_mov_b32 m0, s38
	v_lshl_add_u64 v[178:179], s[88:89], 0, v[196:197]
	ds_read_b128 v[130:133], v213 offset:32768
	ds_read_b128 v[138:141], v213 offset:33792
	ds_read_b128 v[146:149], v213 offset:34816
	ds_read_b128 v[150:153], v213 offset:35840
	ds_read_b128 v[162:165], v213 offset:36864
	ds_read_b128 v[166:169], v213 offset:37888
	ds_read_b128 v[170:173], v213 offset:38912
	ds_read_b128 v[174:177], v213 offset:39936
	global_load_lds_dwordx4 v[178:179], off
	v_lshl_add_u64 v[178:179], s[88:89], 0, v[198:199]
	s_mov_b32 m0, s39
	s_nop 0
	global_load_lds_dwordx4 v[178:179], off
	s_add_i32 s9, 0, 0x1c000
	v_add_u32_e32 v190, s9, v211
	ds_read_b128 v[178:181], v190
	ds_read_b128 v[182:185], v190 offset:1024
	ds_read_b128 v[186:189], v190 offset:2048
	ds_read_b128 v[190:193], v190 offset:3072
	s_waitcnt vmcnt(8)
	s_waitcnt lgkmcnt(0)
	v_mfma_f32_16x16x32_bf16 v[158:161], v[82:85], v[130:133], v[158:161]
	v_mfma_f32_16x16x32_bf16 v[154:157], v[98:101], v[130:133], v[154:157]
	v_mfma_f32_16x16x32_bf16 v[134:137], v[82:85], v[146:149], v[134:137]
	v_mfma_f32_16x16x32_bf16 v[126:129], v[98:101], v[146:149], v[126:129]
	v_mfma_f32_16x16x32_bf16 v[106:109], v[82:85], v[162:165], v[106:109]
	v_mfma_f32_16x16x32_bf16 v[102:105], v[98:101], v[162:165], v[102:105]
	v_mfma_f32_16x16x32_bf16 v[78:81], v[82:85], v[170:173], v[78:81]
	v_mfma_f32_16x16x32_bf16 v[74:77], v[98:101], v[170:173], v[74:77]
	s_barrier
	s_setprio 1
	v_mfma_f32_16x16x32_bf16 v[158:161], v[94:97], v[138:141], v[158:161]
	v_mfma_f32_16x16x32_bf16 v[154:157], v[114:117], v[138:141], v[154:157]
	v_mfma_f32_16x16x32_bf16 v[134:137], v[94:97], v[150:153], v[134:137]
	v_mfma_f32_16x16x32_bf16 v[126:129], v[114:117], v[150:153], v[126:129]
	v_mfma_f32_16x16x32_bf16 v[106:109], v[94:97], v[166:169], v[106:109]
	v_mfma_f32_16x16x32_bf16 v[102:105], v[114:117], v[166:169], v[102:105]
	v_mfma_f32_16x16x32_bf16 v[78:81], v[94:97], v[174:177], v[78:81]
	v_mfma_f32_16x16x32_bf16 v[74:77], v[114:117], v[174:177], v[74:77]
	v_mfma_f32_16x16x32_bf16 v[142:145], v[178:181], v[130:133], v[142:145]
	v_mfma_f32_16x16x32_bf16 v[122:125], v[186:189], v[130:133], v[122:125]
	v_mfma_f32_16x16x32_bf16 v[118:121], v[178:181], v[146:149], v[118:121]
	v_mfma_f32_16x16x32_bf16 v[110:113], v[186:189], v[146:149], v[110:113]
	v_mfma_f32_16x16x32_bf16 v[90:93], v[178:181], v[162:165], v[90:93]
	v_mfma_f32_16x16x32_bf16 v[86:89], v[186:189], v[162:165], v[86:89]
	v_mfma_f32_16x16x32_bf16 v[70:73], v[178:181], v[170:173], v[70:73]
	v_mfma_f32_16x16x32_bf16 v[66:69], v[186:189], v[170:173], v[66:69]
	v_mfma_f32_16x16x32_bf16 v[142:145], v[182:185], v[138:141], v[142:145]
	v_mfma_f32_16x16x32_bf16 v[138:141], v[190:193], v[138:141], v[122:125]
	v_mfma_f32_16x16x32_bf16 v[118:121], v[182:185], v[150:153], v[118:121]
	v_mfma_f32_16x16x32_bf16 v[110:113], v[190:193], v[150:153], v[110:113]
	v_mfma_f32_16x16x32_bf16 v[90:93], v[182:185], v[166:169], v[90:93]
	v_mfma_f32_16x16x32_bf16 v[86:89], v[190:193], v[166:169], v[86:89]
	v_mfma_f32_16x16x32_bf16 v[70:73], v[182:185], v[174:177], v[70:73]
	v_mfma_f32_16x16x32_bf16 v[66:69], v[190:193], v[174:177], v[66:69]
	s_setprio 0
	s_barrier
; #define PG8_STAGE(bufoff, gbase, voff) do { _Pragma("unroll") for (int _i = 0; _i < 2; ++_i) \
;         __builtin_amdgcn_global_load_lds((const unsigned*)((const char*)(gbase) + (voff)[_i]), (LAS unsigned*)(lds + (bufoff) + ldsw + _i * 8192), 16, 0, 0); } while (0)
; #define PG8_LDA(dst, b, h) do { _Pragma("unroll") for (int m = 0; m < 4; ++m) _Pragma("unroll") for (int k = 0; k < 2; ++k) dst[m][k] = *(const LAS bf16x8*)(lds + PG8_SA(b, h) + aoff + m * 2048 + k * 1024); } while (0)
; #define PG8_MMA(ai, bj, At, Bt) do { __builtin_amdgcn_s_setprio(1); _Pragma("unroll") for (int m = 0; m < 4; ++m) _Pragma("unroll") for (int n = 0; n < 2; ++n) _Pragma("unroll") for (int k = 0; k < 2; ++k) \
;         acc[ai][bj][m][n] = __builtin_amdgcn_mfma_f32_16x16x32_bf16(Bt[n][k], At[m][k], acc[ai][bj][m][n], 0, 0, 0); __builtin_amdgcn_s_setprio(0); } while (0)
; #define PG8_WAIT_V(n) asm volatile("s_waitcnt vmcnt(" #n ")" ::: "memory")
; #define PG8_WAIT_L(n) asm volatile("s_waitcnt lgkmcnt(" #n ")" ::: "memory")
; #define PG8_BAR __builtin_amdgcn_s_barrier()
; #define PG8_SCHED __builtin_amdgcn_sched_barrier(0)
; template <class Epi>
; __device__ __forceinline__ void gemm_phase(LAS unsigned char* lds, const Gemm g, const Sched& S, const Epi& E) {
;     ...
;             PG8_LDA(At, 1, 1); PG8_STAGE(PG8_SA(1, 0), a3, voffA);
;             PG8_BAR; PG8_WAIT_L(0); PG8_MMA(1, 0, At, B0); PG8_BAR; PG8_SCHED;
;             PG8_STAGE(PG8_SB(1, 1), b3 + hstepB, voffB);
;             PG8_WAIT_V(6); PG8_BAR; PG8_MMA(1, 1, At, B1); PG8_BAR;
;         }
	s_add_i32 s8, s8, s3
	v_lshl_add_u64 v[194:195], v[194:195], 0, s[60:61]
	s_mov_b32 m0, s8
	s_nop 0
	global_load_lds_dwordx4 v[194:195], off
	v_lshl_add_u64 v[194:195], v[206:207], 0, s[60:61]
	s_add_i32 m0, s8, 0x2000
	s_nop 0
	global_load_lds_dwordx4 v[194:195], off
	s_mov_b32 m0, s40
	v_lshl_add_u64 v[194:195], v[208:209], 0, s[60:61]
	ds_read_b128 v[122:125], v213 offset:49152
	ds_read_b128 v[130:133], v213 offset:50176
	ds_read_b128 v[146:149], v213 offset:51200
	ds_read_b128 v[150:153], v213 offset:52224
	ds_read_b128 v[162:165], v213 offset:53248
	ds_read_b128 v[166:169], v213 offset:54272
	ds_read_b128 v[170:173], v213 offset:55296
	ds_read_b128 v[174:177], v213 offset:56320
	global_load_lds_dwordx4 v[194:195], off
	v_lshl_add_u64 v[194:195], v[214:215], 0, s[60:61]
	s_mov_b32 m0, s41
	s_nop 0
	global_load_lds_dwordx4 v[194:195], off
	s_add_i32 s8, s9, s3
	v_lshl_add_u64 v[194:195], v[216:217], 0, s[60:61]
	s_mov_b32 m0, s8
	s_nop 0
	global_load_lds_dwordx4 v[194:195], off
	v_lshl_add_u64 v[194:195], v[222:223], 0, s[60:61]
	s_add_i32 m0, s8, 0x2000
	s_nop 0
	global_load_lds_dwordx4 v[194:195], off
	s_waitcnt vmcnt(8)
	s_waitcnt lgkmcnt(0)
	v_mfma_f32_16x16x32_bf16 v[62:65], v[82:85], v[122:125], v[62:65]
	v_mfma_f32_16x16x32_bf16 v[58:61], v[98:101], v[122:125], v[58:61]
	v_mfma_f32_16x16x32_bf16 v[46:49], v[82:85], v[146:149], v[46:49]
	v_mfma_f32_16x16x32_bf16 v[42:45], v[98:101], v[146:149], v[42:45]
	v_mfma_f32_16x16x32_bf16 v[30:33], v[82:85], v[162:165], v[30:33]
	v_mfma_f32_16x16x32_bf16 v[26:29], v[98:101], v[162:165], v[26:29]
	v_mfma_f32_16x16x32_bf16 v[14:17], v[82:85], v[170:173], v[14:17]
	v_mfma_f32_16x16x32_bf16 v[10:13], v[98:101], v[170:173], v[10:13]
	s_barrier
	s_setprio 1
	v_mfma_f32_16x16x32_bf16 v[62:65], v[94:97], v[130:133], v[62:65]
	v_mfma_f32_16x16x32_bf16 v[58:61], v[114:117], v[130:133], v[58:61]
	v_mfma_f32_16x16x32_bf16 v[46:49], v[94:97], v[150:153], v[46:49]
	v_mfma_f32_16x16x32_bf16 v[42:45], v[114:117], v[150:153], v[42:45]
	v_mfma_f32_16x16x32_bf16 v[30:33], v[94:97], v[166:169], v[30:33]
	v_mfma_f32_16x16x32_bf16 v[26:29], v[114:117], v[166:169], v[26:29]
	v_mfma_f32_16x16x32_bf16 v[14:17], v[94:97], v[174:177], v[14:17]
	v_mfma_f32_16x16x32_bf16 v[10:13], v[114:117], v[174:177], v[10:13]
	v_mfma_f32_16x16x32_bf16 v[54:57], v[178:181], v[122:125], v[54:57]
	v_mfma_f32_16x16x32_bf16 v[50:53], v[186:189], v[122:125], v[50:53]
	v_mfma_f32_16x16x32_bf16 v[38:41], v[178:181], v[146:149], v[38:41]
	v_mfma_f32_16x16x32_bf16 v[34:37], v[186:189], v[146:149], v[34:37]
	v_mfma_f32_16x16x32_bf16 v[22:25], v[178:181], v[162:165], v[22:25]
	v_mfma_f32_16x16x32_bf16 v[18:21], v[186:189], v[162:165], v[18:21]
	v_mfma_f32_16x16x32_bf16 v[6:9], v[178:181], v[170:173], v[6:9]
	v_mfma_f32_16x16x32_bf16 v[2:5], v[186:189], v[170:173], v[2:5]
	v_mfma_f32_16x16x32_bf16 v[54:57], v[182:185], v[130:133], v[54:57]
	v_mfma_f32_16x16x32_bf16 v[50:53], v[190:193], v[130:133], v[50:53]
	v_mfma_f32_16x16x32_bf16 v[38:41], v[182:185], v[150:153], v[38:41]
	v_mfma_f32_16x16x32_bf16 v[34:37], v[190:193], v[150:153], v[34:37]
	v_mfma_f32_16x16x32_bf16 v[22:25], v[182:185], v[166:169], v[22:25]
	v_mfma_f32_16x16x32_bf16 v[18:21], v[190:193], v[166:169], v[18:21]
	v_mfma_f32_16x16x32_bf16 v[6:9], v[182:185], v[174:177], v[6:9]
	v_mfma_f32_16x16x32_bf16 v[2:5], v[190:193], v[174:177], v[2:5]
	s_setprio 0
	s_add_u32 s4, s4, 0x100
	s_addc_u32 s5, s5, 0
	s_add_u32 s34, s34, 0x100
	s_addc_u32 s35, s35, 0
	s_cmp_ge_u32 s14, s73
	s_mov_b32 s88, s14
	s_barrier
	s_cbranch_scc0 .LBB0_461
	v_readfirstlane_b32 s98, v219
	s_nop 1
	s_bitcmp1_b32 s98, 8
	s_cbranch_scc1 .Lresync_x_461
	s_barrier

; #define PG8_STAGE(bufoff, gbase, voff) do { _Pragma("unroll") for (int _i = 0; _i < 2; ++_i) \
;         __builtin_amdgcn_global_load_lds((const unsigned*)((const char*)(gbase) + (voff)[_i]), (LAS unsigned*)(lds + (bufoff) + ldsw + _i * 8192), 16, 0, 0); } while (0)
; #define PG8_LDA(dst, b, h) do { _Pragma("unroll") for (int m = 0; m < 4; ++m) _Pragma("unroll") for (int k = 0; k < 2; ++k) dst[m][k] = *(const LAS bf16x8*)(lds + PG8_SA(b, h) + aoff + m * 2048 + k * 1024); } while (0)
; #define PG8_LDB(dst, b, h) do { _Pragma("unroll") for (int n = 0; n < 2; ++n) _Pragma("unroll") for (int k = 0; k < 2; ++k) dst[n][k] = *(const LAS bf16x8*)(lds + PG8_SB(b, h) + boff + n * 2048 + k * 1024); } while (0)
; #define PG8_MMA(ai, bj, At, Bt) do { __builtin_amdgcn_s_setprio(1); _Pragma("unroll") for (int m = 0; m < 4; ++m) _Pragma("unroll") for (int n = 0; n < 2; ++n) _Pragma("unroll") for (int k = 0; k < 2; ++k) \
;         acc[ai][bj][m][n] = __builtin_amdgcn_mfma_f32_16x16x32_bf16(Bt[n][k], At[m][k], acc[ai][bj][m][n], 0, 0, 0); __builtin_amdgcn_s_setprio(0); } while (0)
; #define PG8_WAIT_V(n) asm volatile("s_waitcnt vmcnt(" #n ")" ::: "memory")
; #define PG8_WAIT_L(n) asm volatile("s_waitcnt lgkmcnt(" #n ")" ::: "memory")
; #define PG8_BAR __builtin_amdgcn_s_barrier()
; #define PG8_SCHED __builtin_amdgcn_sched_barrier(0)
; template <class Epi>
; __device__ __forceinline__ void gemm_phase(LAS unsigned char* lds, const Gemm g, const Sched& S, const Epi& E) {
;     ...
;             PG8_LDB(B0, 0, 0); PG8_SCHED; PG8_LDA(At, 0, 0); PG8_STAGE(PG8_SA(1, 1), a1 + hstepA, voffA);
;             PG8_WAIT_L(8); PG8_BAR; PG8_WAIT_L(0); PG8_MMA(0, 0, At, B0); PG8_BAR; PG8_SCHED;
;             PG8_LDB(B1, 0, 1); PG8_STAGE(PG8_SB(0, 0), b2, voffB);
;             PG8_BAR; PG8_WAIT_L(0); PG8_MMA(0, 1, At, B1); PG8_BAR;
;             PG8_LDA(At, 0, 1); PG8_STAGE(PG8_SA(0, 0), a2, voffA);
;             PG8_BAR; PG8_WAIT_L(0); PG8_MMA(1, 0, At, B0); PG8_BAR; PG8_SCHED;
;             PG8_STAGE(PG8_SB(0, 1), b2 + hstepB, voffB);
;             PG8_WAIT_V(6); PG8_BAR; PG8_MMA(1, 1, At, B1); PG8_BAR;
.Lresync_y_555:
.LBB0_555:
	s_add_i32 s14, s6, 2
	s_add_u32 s8, s4, 0x80
	s_addc_u32 s7, s5, 0
	s_add_i32 s9, 0, 0x10000
	v_add_u32_e32 v160, s9, v156
	ds_read_b128 v[142:145], v160
	ds_read_b128 v[146:149], v160 offset:1024
	ds_read_b128 v[150:153], v160 offset:2048
	ds_read_b128 v[160:163], v160 offset:3072
	s_cmp_eq_u32 s43, s6
	s_cselect_b32 s6, s57, s8
	s_cselect_b32 s7, s55, s7
	s_cselect_b32 s91, s59, s35
	s_cselect_b32 s90, s95, s34
	v_lshl_add_u64 v[192:193], s[4:5], 0, v[136:137]
	s_add_i32 m0, s33, 0xc000
	ds_read_b128 v[164:167], v159
	ds_read_b128 v[168:171], v159 offset:1024
	ds_read_b128 v[172:175], v159 offset:2048
	ds_read_b128 v[176:179], v159 offset:3072
	ds_read_b128 v[180:183], v159 offset:4096
	ds_read_b128 v[184:187], v159 offset:5120
	ds_read_b128 v[188:191], v159 offset:6144
	ds_read_b128 v[196:199], v159 offset:7168
	global_load_lds_dwordx4 v[192:193], off
	v_lshl_add_u64 v[192:193], s[4:5], 0, v[138:139]
	s_add_i32 m0, s33, 0xe000
	s_nop 0
	global_load_lds_dwordx4 v[192:193], off
	s_add_i32 s8, 0, 0x14000
	v_add_u32_e32 v192, s8, v156
	ds_read_b128 v[200:203], v192
	ds_read_b128 v[204:207], v192 offset:1024
	ds_read_b128 v[208:211], v192 offset:2048
	ds_read_b128 v[212:215], v192 offset:3072
	s_waitcnt vmcnt(8)
	s_waitcnt lgkmcnt(0)
	v_mfma_f32_16x16x32_bf16 v[126:129], v[142:145], v[164:167], v[126:129]
	v_mfma_f32_16x16x32_bf16 v[122:125], v[150:153], v[164:167], v[122:125]
	v_mfma_f32_16x16x32_bf16 v[110:113], v[142:145], v[172:175], v[110:113]
	v_mfma_f32_16x16x32_bf16 v[106:109], v[150:153], v[172:175], v[106:109]
	v_mfma_f32_16x16x32_bf16 v[94:97], v[142:145], v[180:183], v[94:97]
	v_mfma_f32_16x16x32_bf16 v[90:93], v[150:153], v[180:183], v[90:93]
	v_mfma_f32_16x16x32_bf16 v[78:81], v[142:145], v[188:191], v[78:81]
	v_mfma_f32_16x16x32_bf16 v[74:77], v[150:153], v[188:191], v[74:77]
	s_barrier
	s_setprio 1
	v_mfma_f32_16x16x32_bf16 v[126:129], v[146:149], v[168:171], v[126:129]
	v_mfma_f32_16x16x32_bf16 v[122:125], v[160:163], v[168:171], v[122:125]
	v_mfma_f32_16x16x32_bf16 v[110:113], v[146:149], v[176:179], v[110:113]
	v_mfma_f32_16x16x32_bf16 v[106:109], v[160:163], v[176:179], v[106:109]
	v_mfma_f32_16x16x32_bf16 v[94:97], v[146:149], v[184:187], v[94:97]
	v_mfma_f32_16x16x32_bf16 v[90:93], v[160:163], v[184:187], v[90:93]
	v_mfma_f32_16x16x32_bf16 v[78:81], v[146:149], v[196:199], v[78:81]
	v_mfma_f32_16x16x32_bf16 v[74:77], v[160:163], v[196:199], v[74:77]
	v_mfma_f32_16x16x32_bf16 v[118:121], v[200:203], v[164:167], v[118:121]
	v_mfma_f32_16x16x32_bf16 v[114:117], v[208:211], v[164:167], v[114:117]
	v_mfma_f32_16x16x32_bf16 v[102:105], v[200:203], v[172:175], v[102:105]
	v_mfma_f32_16x16x32_bf16 v[98:101], v[208:211], v[172:175], v[98:101]
	v_mfma_f32_16x16x32_bf16 v[86:89], v[200:203], v[180:183], v[86:89]
	v_mfma_f32_16x16x32_bf16 v[82:85], v[208:211], v[180:183], v[82:85]
	v_mfma_f32_16x16x32_bf16 v[70:73], v[200:203], v[188:191], v[70:73]
	v_mfma_f32_16x16x32_bf16 v[66:69], v[208:211], v[188:191], v[66:69]
	v_mfma_f32_16x16x32_bf16 v[118:121], v[204:207], v[168:171], v[118:121]
	v_mfma_f32_16x16x32_bf16 v[114:117], v[212:215], v[168:171], v[114:117]
	v_mfma_f32_16x16x32_bf16 v[102:105], v[204:207], v[176:179], v[102:105]
	v_mfma_f32_16x16x32_bf16 v[98:101], v[212:215], v[176:179], v[98:101]
	v_mfma_f32_16x16x32_bf16 v[86:89], v[204:207], v[184:187], v[86:89]
	v_mfma_f32_16x16x32_bf16 v[82:85], v[212:215], v[184:187], v[82:85]
	v_mfma_f32_16x16x32_bf16 v[70:73], v[204:207], v[196:199], v[70:73]
	v_mfma_f32_16x16x32_bf16 v[66:69], v[212:215], v[196:199], v[66:69]
	s_setprio 0
	s_barrier
	s_add_i32 s9, s9, s3
	v_lshl_add_u64 v[192:193], s[90:91], 0, v[0:1]
	s_mov_b32 m0, s9
	v_lshl_add_u64 v[194:195], s[90:91], 0, v[134:135]
	global_load_lds_dwordx4 v[192:193], off
	s_add_i32 m0, s9, 0x2000
	s_nop 0
	global_load_lds_dwordx4 v[194:195], off
	s_mov_b32 m0, s33
	v_lshl_add_u64 v[216:217], s[6:7], 0, v[130:131]
	ds_read_b128 v[164:167], v159 offset:16384
	ds_read_b128 v[168:171], v159 offset:17408
	ds_read_b128 v[172:175], v159 offset:18432
	ds_read_b128 v[176:179], v159 offset:19456
	ds_read_b128 v[180:183], v159 offset:20480
	ds_read_b128 v[184:187], v159 offset:21504
	ds_read_b128 v[188:191], v159 offset:22528
	ds_read_b128 v[196:199], v159 offset:23552
	global_load_lds_dwordx4 v[216:217], off
	v_lshl_add_u64 v[222:223], s[6:7], 0, v[132:133]
	s_mov_b32 m0, s38
	s_nop 0
	global_load_lds_dwordx4 v[222:223], off
	s_add_u32 s90, s90, s76
	s_addc_u32 s91, s91, s77
	s_add_i32 s8, s8, s3
	v_lshl_add_u64 v[224:225], s[90:91], 0, v[0:1]
	s_mov_b32 m0, s8
	v_lshl_add_u64 v[226:227], s[90:91], 0, v[134:135]
	global_load_lds_dwordx4 v[224:225], off
	s_add_i32 m0, s8, 0x2000
	s_nop 0
	global_load_lds_dwordx4 v[226:227], off
	s_waitcnt vmcnt(8)
	s_waitcnt lgkmcnt(0)
	v_mfma_f32_16x16x32_bf16 v[62:65], v[142:145], v[164:167], v[62:65]
	v_mfma_f32_16x16x32_bf16 v[58:61], v[150:153], v[164:167], v[58:61]
	v_mfma_f32_16x16x32_bf16 v[46:49], v[142:145], v[172:175], v[46:49]
	v_mfma_f32_16x16x32_bf16 v[42:45], v[150:153], v[172:175], v[42:45]
	v_mfma_f32_16x16x32_bf16 v[30:33], v[142:145], v[180:183], v[30:33]
	v_mfma_f32_16x16x32_bf16 v[26:29], v[150:153], v[180:183], v[26:29]
	v_mfma_f32_16x16x32_bf16 v[14:17], v[142:145], v[188:191], v[14:17]
	v_mfma_f32_16x16x32_bf16 v[10:13], v[150:153], v[188:191], v[10:13]
	s_barrier
; #define PG8_STAGE(bufoff, gbase, voff) do { _Pragma("unroll") for (int _i = 0; _i < 2; ++_i) \
;         __builtin_amdgcn_global_load_lds((const unsigned*)((const char*)(gbase) + (voff)[_i]), (LAS unsigned*)(lds + (bufoff) + ldsw + _i * 8192), 16, 0, 0); } while (0)
; #define PG8_LDA(dst, b, h) do { _Pragma("unroll") for (int m = 0; m < 4; ++m) _Pragma("unroll") for (int k = 0; k < 2; ++k) dst[m][k] = *(const LAS bf16x8*)(lds + PG8_SA(b, h) + aoff + m * 2048 + k * 1024); } while (0)
; #define PG8_LDB(dst, b, h) do { _Pragma("unroll") for (int n = 0; n < 2; ++n) _Pragma("unroll") for (int k = 0; k < 2; ++k) dst[n][k] = *(const LAS bf16x8*)(lds + PG8_SB(b, h) + boff + n * 2048 + k * 1024); } while (0)
; #define PG8_MMA(ai, bj, At, Bt) do { __builtin_amdgcn_s_setprio(1); _Pragma("unroll") for (int m = 0; m < 4; ++m) _Pragma("unroll") for (int n = 0; n < 2; ++n) _Pragma("unroll") for (int k = 0; k < 2; ++k) \
;         acc[ai][bj][m][n] = __builtin_amdgcn_mfma_f32_16x16x32_bf16(Bt[n][k], At[m][k], acc[ai][bj][m][n], 0, 0, 0); __builtin_amdgcn_s_setprio(0); } while (0)
; #define PG8_WAIT_V(n) asm volatile("s_waitcnt vmcnt(" #n ")" ::: "memory")
; #define PG8_WAIT_L(n) asm volatile("s_waitcnt lgkmcnt(" #n ")" ::: "memory")
; #define PG8_BAR __builtin_amdgcn_s_barrier()
; #define PG8_SCHED __builtin_amdgcn_sched_barrier(0)
; template <class Epi>
; __device__ __forceinline__ void gemm_phase(LAS unsigned char* lds, const Gemm g, const Sched& S, const Epi& E) {
;     ...
;             PG8_WAIT_V(6); PG8_BAR; PG8_MMA(1, 1, At, B1); PG8_BAR;
;             PG8_LDB(B0, 1, 0); PG8_SCHED; PG8_LDA(At, 1, 0); PG8_STAGE(PG8_SA(0, 1), a2 + hstepA, voffA);
;             PG8_WAIT_L(8); PG8_BAR; PG8_WAIT_L(0); PG8_MMA(0, 0, At, B0); PG8_BAR; PG8_SCHED;
;             PG8_LDB(B1, 1, 1); PG8_STAGE(PG8_SB(1, 0), b3, voffB);
;             PG8_BAR; PG8_WAIT_L(0); PG8_MMA(0, 1, At, B1); PG8_BAR;
;             PG8_LDA(At, 1, 1); PG8_STAGE(PG8_SA(1, 0), a3, voffA);
;             PG8_BAR; PG8_WAIT_L(0); PG8_MMA(1, 0, At, B0); PG8_BAR; PG8_SCHED;
	s_setprio 1
	v_mfma_f32_16x16x32_bf16 v[62:65], v[146:149], v[168:171], v[62:65]
	v_mfma_f32_16x16x32_bf16 v[58:61], v[160:163], v[168:171], v[58:61]
	v_mfma_f32_16x16x32_bf16 v[46:49], v[146:149], v[176:179], v[46:49]
	v_mfma_f32_16x16x32_bf16 v[42:45], v[160:163], v[176:179], v[42:45]
	v_mfma_f32_16x16x32_bf16 v[30:33], v[146:149], v[184:187], v[30:33]
	v_mfma_f32_16x16x32_bf16 v[26:29], v[160:163], v[184:187], v[26:29]
	v_mfma_f32_16x16x32_bf16 v[14:17], v[146:149], v[196:199], v[14:17]
	v_mfma_f32_16x16x32_bf16 v[10:13], v[160:163], v[196:199], v[10:13]
	v_mfma_f32_16x16x32_bf16 v[54:57], v[200:203], v[164:167], v[54:57]
	v_mfma_f32_16x16x32_bf16 v[50:53], v[208:211], v[164:167], v[50:53]
	v_mfma_f32_16x16x32_bf16 v[38:41], v[200:203], v[172:175], v[38:41]
	v_mfma_f32_16x16x32_bf16 v[34:37], v[208:211], v[172:175], v[34:37]
	v_mfma_f32_16x16x32_bf16 v[22:25], v[200:203], v[180:183], v[22:25]
	v_mfma_f32_16x16x32_bf16 v[18:21], v[208:211], v[180:183], v[18:21]
	v_mfma_f32_16x16x32_bf16 v[6:9], v[200:203], v[188:191], v[6:9]
	v_mfma_f32_16x16x32_bf16 v[2:5], v[208:211], v[188:191], v[2:5]
	v_mfma_f32_16x16x32_bf16 v[54:57], v[204:207], v[168:171], v[54:57]
	v_mfma_f32_16x16x32_bf16 v[50:53], v[212:215], v[168:171], v[50:53]
	v_mfma_f32_16x16x32_bf16 v[38:41], v[204:207], v[176:179], v[38:41]
	v_mfma_f32_16x16x32_bf16 v[34:37], v[212:215], v[176:179], v[34:37]
	v_mfma_f32_16x16x32_bf16 v[22:25], v[204:207], v[184:187], v[22:25]
	v_mfma_f32_16x16x32_bf16 v[18:21], v[212:215], v[184:187], v[18:21]
	v_mfma_f32_16x16x32_bf16 v[6:9], v[204:207], v[196:199], v[6:9]
	v_mfma_f32_16x16x32_bf16 v[2:5], v[212:215], v[196:199], v[2:5]
	s_setprio 0
	s_barrier
	s_add_i32 s8, 0, 0x18000
	v_add_u32_e32 v160, s8, v156
	ds_read_b128 v[142:145], v160
	ds_read_b128 v[146:149], v160 offset:1024
	ds_read_b128 v[150:153], v160 offset:2048
	ds_read_b128 v[160:163], v160 offset:3072
	s_add_u32 s6, s6, s36
	s_addc_u32 s7, s7, s37
	s_mov_b32 m0, s39
	v_lshl_add_u64 v[200:201], s[6:7], 0, v[130:131]
	ds_read_b128 v[164:167], v159 offset:32768
	ds_read_b128 v[168:171], v159 offset:33792
	ds_read_b128 v[172:175], v159 offset:34816
	ds_read_b128 v[176:179], v159 offset:35840
	ds_read_b128 v[180:183], v159 offset:36864
	ds_read_b128 v[184:187], v159 offset:37888
	ds_read_b128 v[188:191], v159 offset:38912
	ds_read_b128 v[196:199], v159 offset:39936
	global_load_lds_dwordx4 v[200:201], off
	v_lshl_add_u64 v[200:201], s[6:7], 0, v[132:133]
	s_mov_b32 m0, s40
	s_nop 0
	global_load_lds_dwordx4 v[200:201], off
	s_add_i32 s6, 0, 0x1c000
	v_add_u32_e32 v212, s6, v156
	ds_read_b128 v[200:203], v212
	ds_read_b128 v[204:207], v212 offset:1024
	ds_read_b128 v[208:211], v212 offset:2048
	ds_read_b128 v[212:215], v212 offset:3072
	s_waitcnt vmcnt(8)
	s_waitcnt lgkmcnt(0)
	v_mfma_f32_16x16x32_bf16 v[126:129], v[142:145], v[164:167], v[126:129]
	v_mfma_f32_16x16x32_bf16 v[122:125], v[150:153], v[164:167], v[122:125]
	v_mfma_f32_16x16x32_bf16 v[110:113], v[142:145], v[172:175], v[110:113]
	v_mfma_f32_16x16x32_bf16 v[106:109], v[150:153], v[172:175], v[106:109]
	v_mfma_f32_16x16x32_bf16 v[94:97], v[142:145], v[180:183], v[94:97]
	v_mfma_f32_16x16x32_bf16 v[90:93], v[150:153], v[180:183], v[90:93]
	v_mfma_f32_16x16x32_bf16 v[78:81], v[142:145], v[188:191], v[78:81]
	v_mfma_f32_16x16x32_bf16 v[74:77], v[150:153], v[188:191], v[74:77]
	s_barrier
	s_setprio 1
	v_mfma_f32_16x16x32_bf16 v[126:129], v[146:149], v[168:171], v[126:129]
	v_mfma_f32_16x16x32_bf16 v[122:125], v[160:163], v[168:171], v[122:125]
	v_mfma_f32_16x16x32_bf16 v[110:113], v[146:149], v[176:179], v[110:113]
	v_mfma_f32_16x16x32_bf16 v[106:109], v[160:163], v[176:179], v[106:109]
	v_mfma_f32_16x16x32_bf16 v[94:97], v[146:149], v[184:187], v[94:97]
	v_mfma_f32_16x16x32_bf16 v[90:93], v[160:163], v[184:187], v[90:93]
	v_mfma_f32_16x16x32_bf16 v[78:81], v[146:149], v[196:199], v[78:81]
	v_mfma_f32_16x16x32_bf16 v[74:77], v[160:163], v[196:199], v[74:77]
	v_mfma_f32_16x16x32_bf16 v[118:121], v[200:203], v[164:167], v[118:121]
	v_mfma_f32_16x16x32_bf16 v[114:117], v[208:211], v[164:167], v[114:117]
	v_mfma_f32_16x16x32_bf16 v[102:105], v[200:203], v[172:175], v[102:105]
	v_mfma_f32_16x16x32_bf16 v[98:101], v[208:211], v[172:175], v[98:101]
	v_mfma_f32_16x16x32_bf16 v[86:89], v[200:203], v[180:183], v[86:89]
	v_mfma_f32_16x16x32_bf16 v[82:85], v[208:211], v[180:183], v[82:85]
	v_mfma_f32_16x16x32_bf16 v[70:73], v[200:203], v[188:191], v[70:73]
	v_mfma_f32_16x16x32_bf16 v[66:69], v[208:211], v[188:191], v[66:69]
	v_mfma_f32_16x16x32_bf16 v[118:121], v[204:207], v[168:171], v[118:121]
	v_mfma_f32_16x16x32_bf16 v[114:117], v[212:215], v[168:171], v[114:117]
	v_mfma_f32_16x16x32_bf16 v[102:105], v[204:207], v[176:179], v[102:105]
	v_mfma_f32_16x16x32_bf16 v[98:101], v[212:215], v[176:179], v[98:101]
	v_mfma_f32_16x16x32_bf16 v[86:89], v[204:207], v[184:187], v[86:89]
	v_mfma_f32_16x16x32_bf16 v[82:85], v[212:215], v[184:187], v[82:85]
	v_mfma_f32_16x16x32_bf16 v[70:73], v[204:207], v[196:199], v[70:73]
	v_mfma_f32_16x16x32_bf16 v[66:69], v[212:215], v[196:199], v[66:69]
	s_setprio 0
	s_barrier
; #define PG8_STAGE(bufoff, gbase, voff) do { _Pragma("unroll") for (int _i = 0; _i < 2; ++_i) \
;         __builtin_amdgcn_global_load_lds((const unsigned*)((const char*)(gbase) + (voff)[_i]), (LAS unsigned*)(lds + (bufoff) + ldsw + _i * 8192), 16, 0, 0); } while (0)
; #define PG8_LDA(dst, b, h) do { _Pragma("unroll") for (int m = 0; m < 4; ++m) _Pragma("unroll") for (int k = 0; k < 2; ++k) dst[m][k] = *(const LAS bf16x8*)(lds + PG8_SA(b, h) + aoff + m * 2048 + k * 1024); } while (0)
; #define PG8_MMA(ai, bj, At, Bt) do { __builtin_amdgcn_s_setprio(1); _Pragma("unroll") for (int m = 0; m < 4; ++m) _Pragma("unroll") for (int n = 0; n < 2; ++n) _Pragma("unroll") for (int k = 0; k < 2; ++k) \
;         acc[ai][bj][m][n] = __builtin_amdgcn_mfma_f32_16x16x32_bf16(Bt[n][k], At[m][k], acc[ai][bj][m][n], 0, 0, 0); __builtin_amdgcn_s_setprio(0); } while (0)
; #define PG8_WAIT_V(n) asm volatile("s_waitcnt vmcnt(" #n ")" ::: "memory")
; #define PG8_WAIT_L(n) asm volatile("s_waitcnt lgkmcnt(" #n ")" ::: "memory")
; #define PG8_BAR __builtin_amdgcn_s_barrier()
; #define PG8_SCHED __builtin_amdgcn_sched_barrier(0)
; template <class Epi>
; __device__ __forceinline__ void gemm_phase(LAS unsigned char* lds, const Gemm g, const Sched& S, const Epi& E) {
;     ...
;             PG8_LDA(At, 1, 1); PG8_STAGE(PG8_SA(1, 0), a3, voffA);
;             PG8_BAR; PG8_WAIT_L(0); PG8_MMA(1, 0, At, B0); PG8_BAR; PG8_SCHED;
;             PG8_STAGE(PG8_SB(1, 1), b3 + hstepB, voffB);
;             PG8_WAIT_V(6); PG8_BAR; PG8_MMA(1, 1, At, B1); PG8_BAR;
;         }
	s_add_i32 s7, s8, s3
	v_lshl_add_u64 v[192:193], v[192:193], 0, s[60:61]
	s_mov_b32 m0, s7
	s_nop 0
	global_load_lds_dwordx4 v[192:193], off
	v_lshl_add_u64 v[192:193], v[194:195], 0, s[60:61]
	s_add_i32 m0, s7, 0x2000
	s_nop 0
	global_load_lds_dwordx4 v[192:193], off
	s_mov_b32 m0, s41
	v_lshl_add_u64 v[192:193], v[216:217], 0, s[60:61]
	ds_read_b128 v[164:167], v159 offset:49152
	ds_read_b128 v[168:171], v159 offset:50176
	ds_read_b128 v[172:175], v159 offset:51200
	ds_read_b128 v[176:179], v159 offset:52224
	ds_read_b128 v[180:183], v159 offset:53248
	ds_read_b128 v[184:187], v159 offset:54272
	ds_read_b128 v[188:191], v159 offset:55296
	ds_read_b128 v[196:199], v159 offset:56320
	global_load_lds_dwordx4 v[192:193], off
	v_lshl_add_u64 v[192:193], v[222:223], 0, s[60:61]
	s_mov_b32 m0, s42
	s_nop 0
	global_load_lds_dwordx4 v[192:193], off
	s_add_i32 s6, s6, s3
	v_lshl_add_u64 v[192:193], v[224:225], 0, s[60:61]
	s_mov_b32 m0, s6
	s_nop 0
	global_load_lds_dwordx4 v[192:193], off
	v_lshl_add_u64 v[192:193], v[226:227], 0, s[60:61]
	s_add_i32 m0, s6, 0x2000
	s_nop 0
	global_load_lds_dwordx4 v[192:193], off
	s_waitcnt vmcnt(8)
	s_waitcnt lgkmcnt(0)
	v_mfma_f32_16x16x32_bf16 v[62:65], v[142:145], v[164:167], v[62:65]
	v_mfma_f32_16x16x32_bf16 v[58:61], v[150:153], v[164:167], v[58:61]
	v_mfma_f32_16x16x32_bf16 v[46:49], v[142:145], v[172:175], v[46:49]
	v_mfma_f32_16x16x32_bf16 v[42:45], v[150:153], v[172:175], v[42:45]
	v_mfma_f32_16x16x32_bf16 v[30:33], v[142:145], v[180:183], v[30:33]
	v_mfma_f32_16x16x32_bf16 v[26:29], v[150:153], v[180:183], v[26:29]
	v_mfma_f32_16x16x32_bf16 v[14:17], v[142:145], v[188:191], v[14:17]
	v_mfma_f32_16x16x32_bf16 v[10:13], v[150:153], v[188:191], v[10:13]
	s_barrier
	s_setprio 1
	v_mfma_f32_16x16x32_bf16 v[62:65], v[146:149], v[168:171], v[62:65]
	v_mfma_f32_16x16x32_bf16 v[58:61], v[160:163], v[168:171], v[58:61]
	v_mfma_f32_16x16x32_bf16 v[46:49], v[146:149], v[176:179], v[46:49]
	v_mfma_f32_16x16x32_bf16 v[42:45], v[160:163], v[176:179], v[42:45]
	v_mfma_f32_16x16x32_bf16 v[30:33], v[146:149], v[184:187], v[30:33]
	v_mfma_f32_16x16x32_bf16 v[26:29], v[160:163], v[184:187], v[26:29]
	v_mfma_f32_16x16x32_bf16 v[14:17], v[146:149], v[196:199], v[14:17]
	v_mfma_f32_16x16x32_bf16 v[10:13], v[160:163], v[196:199], v[10:13]
	v_mfma_f32_16x16x32_bf16 v[54:57], v[200:203], v[164:167], v[54:57]
	v_mfma_f32_16x16x32_bf16 v[50:53], v[208:211], v[164:167], v[50:53]
	v_mfma_f32_16x16x32_bf16 v[38:41], v[200:203], v[172:175], v[38:41]
	v_mfma_f32_16x16x32_bf16 v[34:37], v[208:211], v[172:175], v[34:37]
	v_mfma_f32_16x16x32_bf16 v[22:25], v[200:203], v[180:183], v[22:25]
	v_mfma_f32_16x16x32_bf16 v[18:21], v[208:211], v[180:183], v[18:21]
	v_mfma_f32_16x16x32_bf16 v[6:9], v[200:203], v[188:191], v[6:9]
	v_mfma_f32_16x16x32_bf16 v[2:5], v[208:211], v[188:191], v[2:5]
	v_mfma_f32_16x16x32_bf16 v[54:57], v[204:207], v[168:171], v[54:57]
	v_mfma_f32_16x16x32_bf16 v[50:53], v[212:215], v[168:171], v[50:53]
	v_mfma_f32_16x16x32_bf16 v[38:41], v[204:207], v[176:179], v[38:41]
	v_mfma_f32_16x16x32_bf16 v[34:37], v[212:215], v[176:179], v[34:37]
	v_mfma_f32_16x16x32_bf16 v[22:25], v[204:207], v[184:187], v[22:25]
	v_mfma_f32_16x16x32_bf16 v[18:21], v[212:215], v[184:187], v[18:21]
	v_mfma_f32_16x16x32_bf16 v[6:9], v[204:207], v[196:199], v[6:9]
	v_mfma_f32_16x16x32_bf16 v[2:5], v[212:215], v[196:199], v[2:5]
	s_setprio 0
	s_add_u32 s4, s4, 0x100
	s_addc_u32 s5, s5, 0
	s_add_u32 s34, s34, 0x100
	s_addc_u32 s35, s35, 0
	s_cmp_ge_u32 s14, s73
	s_mov_b32 s6, s14
	s_barrier
	s_cbranch_scc0 .LBB0_555
	v_readfirstlane_b32 s98, v219
	s_nop 1
	s_bitcmp1_b32 s98, 8
	s_cbranch_scc1 .Lresync_x_555
	s_barrier

; #define PG8_STAGE(bufoff, gbase, voff) do { _Pragma("unroll") for (int _i = 0; _i < 2; ++_i) \
;         __builtin_amdgcn_global_load_lds((const unsigned*)((const char*)(gbase) + (voff)[_i]), (LAS unsigned*)(lds + (bufoff) + ldsw + _i * 8192), 16, 0, 0); } while (0)
; #define PG8_LDA(dst, b, h) do { _Pragma("unroll") for (int m = 0; m < 4; ++m) _Pragma("unroll") for (int k = 0; k < 2; ++k) dst[m][k] = *(const LAS bf16x8*)(lds + PG8_SA(b, h) + aoff + m * 2048 + k * 1024); } while (0)
; #define PG8_LDB(dst, b, h) do { _Pragma("unroll") for (int n = 0; n < 2; ++n) _Pragma("unroll") for (int k = 0; k < 2; ++k) dst[n][k] = *(const LAS bf16x8*)(lds + PG8_SB(b, h) + boff + n * 2048 + k * 1024); } while (0)
; #define PG8_MMA(ai, bj, At, Bt) do { __builtin_amdgcn_s_setprio(1); _Pragma("unroll") for (int m = 0; m < 4; ++m) _Pragma("unroll") for (int n = 0; n < 2; ++n) _Pragma("unroll") for (int k = 0; k < 2; ++k) \
;         acc[ai][bj][m][n] = __builtin_amdgcn_mfma_f32_16x16x32_bf16(Bt[n][k], At[m][k], acc[ai][bj][m][n], 0, 0, 0); __builtin_amdgcn_s_setprio(0); } while (0)
; #define PG8_WAIT_V(n) asm volatile("s_waitcnt vmcnt(" #n ")" ::: "memory")
; #define PG8_WAIT_L(n) asm volatile("s_waitcnt lgkmcnt(" #n ")" ::: "memory")
; #define PG8_BAR __builtin_amdgcn_s_barrier()
; #define PG8_SCHED __builtin_amdgcn_sched_barrier(0)
; template <class Epi>
; __device__ __forceinline__ void gemm_phase(LAS unsigned char* lds, const Gemm g, const Sched& S, const Epi& E) {
;     ...
;             PG8_LDB(B0, 0, 0); PG8_SCHED; PG8_LDA(At, 0, 0); PG8_STAGE(PG8_SA(1, 1), a1 + hstepA, voffA);
;             PG8_WAIT_L(8); PG8_BAR; PG8_WAIT_L(0); PG8_MMA(0, 0, At, B0); PG8_BAR; PG8_SCHED;
;             PG8_LDB(B1, 0, 1); PG8_STAGE(PG8_SB(0, 0), b2, voffB);
;             PG8_BAR; PG8_WAIT_L(0); PG8_MMA(0, 1, At, B1); PG8_BAR;
;             PG8_LDA(At, 0, 1); PG8_STAGE(PG8_SA(0, 0), a2, voffA);
;             PG8_BAR; PG8_WAIT_L(0); PG8_MMA(1, 0, At, B0); PG8_BAR; PG8_SCHED;
;             PG8_STAGE(PG8_SB(0, 1), b2 + hstepB, voffB);
;             PG8_WAIT_V(6); PG8_BAR; PG8_MMA(1, 1, At, B1); PG8_BAR;
.Lresync_y_649:
.LBB0_649:
	s_add_i32 s14, s4, 2
	s_add_u32 s8, s0, 0x80
	s_addc_u32 s5, s1, 0
	s_add_i32 s9, 0, 0x10000
	v_add_u32_e32 v144, s9, v236
	ds_read_b128 v[132:135], v144
	ds_read_b128 v[136:139], v144 offset:1024
	ds_read_b128 v[140:143], v144 offset:2048
	ds_read_b128 v[144:147], v144 offset:3072
	s_cmp_eq_u32 s95, s4
	s_cselect_b32 s4, s48, s8
	s_cselect_b32 s5, s33, s5
	s_cselect_b32 s87, s51, s35
	s_cselect_b32 s86, s55, s34
	v_lshl_add_u64 v[176:177], s[0:1], 0, v[188:189]
	s_add_i32 m0, s89, 0xc000
	ds_read_b128 v[148:151], v239
	ds_read_b128 v[152:155], v239 offset:1024
	ds_read_b128 v[156:159], v239 offset:2048
	ds_read_b128 v[160:163], v239 offset:3072
	ds_read_b128 v[164:167], v239 offset:4096
	ds_read_b128 v[168:171], v239 offset:5120
	ds_read_b128 v[172:175], v239 offset:6144
	ds_read_b128 v[196:199], v239 offset:7168
	global_load_lds_dwordx4 v[176:177], off
	v_lshl_add_u64 v[176:177], s[0:1], 0, v[190:191]
	s_add_i32 m0, s89, 0xe000
	s_nop 0
	global_load_lds_dwordx4 v[176:177], off
	s_add_i32 s8, 0, 0x14000
	v_add_u32_e32 v176, s8, v236
	ds_read_b128 v[200:203], v176
	ds_read_b128 v[204:207], v176 offset:1024
	ds_read_b128 v[208:211], v176 offset:2048
	ds_read_b128 v[212:215], v176 offset:3072
	s_waitcnt vmcnt(8)
	s_waitcnt lgkmcnt(0)
	v_mfma_f32_16x16x32_bf16 v[126:129], v[132:135], v[148:151], v[126:129]
	v_mfma_f32_16x16x32_bf16 v[122:125], v[140:143], v[148:151], v[122:125]
	v_mfma_f32_16x16x32_bf16 v[110:113], v[132:135], v[156:159], v[110:113]
	v_mfma_f32_16x16x32_bf16 v[106:109], v[140:143], v[156:159], v[106:109]
	v_mfma_f32_16x16x32_bf16 v[94:97], v[132:135], v[164:167], v[94:97]
	v_mfma_f32_16x16x32_bf16 v[90:93], v[140:143], v[164:167], v[90:93]
	v_mfma_f32_16x16x32_bf16 v[78:81], v[132:135], v[172:175], v[78:81]
	v_mfma_f32_16x16x32_bf16 v[74:77], v[140:143], v[172:175], v[74:77]
	s_barrier
	s_setprio 1
	v_mfma_f32_16x16x32_bf16 v[126:129], v[136:139], v[152:155], v[126:129]
	v_mfma_f32_16x16x32_bf16 v[122:125], v[144:147], v[152:155], v[122:125]
	v_mfma_f32_16x16x32_bf16 v[110:113], v[136:139], v[160:163], v[110:113]
	v_mfma_f32_16x16x32_bf16 v[106:109], v[144:147], v[160:163], v[106:109]
	v_mfma_f32_16x16x32_bf16 v[94:97], v[136:139], v[168:171], v[94:97]
	v_mfma_f32_16x16x32_bf16 v[90:93], v[144:147], v[168:171], v[90:93]
	v_mfma_f32_16x16x32_bf16 v[78:81], v[136:139], v[196:199], v[78:81]
	v_mfma_f32_16x16x32_bf16 v[74:77], v[144:147], v[196:199], v[74:77]
	v_mfma_f32_16x16x32_bf16 v[118:121], v[200:203], v[148:151], v[118:121]
	v_mfma_f32_16x16x32_bf16 v[114:117], v[208:211], v[148:151], v[114:117]
	v_mfma_f32_16x16x32_bf16 v[102:105], v[200:203], v[156:159], v[102:105]
	v_mfma_f32_16x16x32_bf16 v[98:101], v[208:211], v[156:159], v[98:101]
	v_mfma_f32_16x16x32_bf16 v[86:89], v[200:203], v[164:167], v[86:89]
	v_mfma_f32_16x16x32_bf16 v[82:85], v[208:211], v[164:167], v[82:85]
	v_mfma_f32_16x16x32_bf16 v[70:73], v[200:203], v[172:175], v[70:73]
	v_mfma_f32_16x16x32_bf16 v[66:69], v[208:211], v[172:175], v[66:69]
	v_mfma_f32_16x16x32_bf16 v[118:121], v[204:207], v[152:155], v[118:121]
	v_mfma_f32_16x16x32_bf16 v[114:117], v[212:215], v[152:155], v[114:117]
	v_mfma_f32_16x16x32_bf16 v[102:105], v[204:207], v[160:163], v[102:105]
	v_mfma_f32_16x16x32_bf16 v[98:101], v[212:215], v[160:163], v[98:101]
	v_mfma_f32_16x16x32_bf16 v[86:89], v[204:207], v[168:171], v[86:89]
	v_mfma_f32_16x16x32_bf16 v[82:85], v[212:215], v[168:171], v[82:85]
	v_mfma_f32_16x16x32_bf16 v[70:73], v[204:207], v[196:199], v[70:73]
	v_mfma_f32_16x16x32_bf16 v[66:69], v[212:215], v[196:199], v[66:69]
	s_setprio 0
	s_barrier
	s_add_i32 s9, s9, s88
	v_lshl_add_u64 v[176:177], s[86:87], 0, v[180:181]
	s_mov_b32 m0, s9
	v_lshl_add_u64 v[192:193], s[86:87], 0, v[184:185]
	global_load_lds_dwordx4 v[176:177], off
	s_add_i32 m0, s9, 0x2000
	s_nop 0
	global_load_lds_dwordx4 v[192:193], off
	s_mov_b32 m0, s89
	v_lshl_add_u64 v[194:195], s[4:5], 0, v[178:179]
	ds_read_b128 v[148:151], v239 offset:16384
	ds_read_b128 v[152:155], v239 offset:17408
	ds_read_b128 v[156:159], v239 offset:18432
	ds_read_b128 v[160:163], v239 offset:19456
	ds_read_b128 v[164:167], v239 offset:20480
	ds_read_b128 v[168:171], v239 offset:21504
	ds_read_b128 v[172:175], v239 offset:22528
	ds_read_b128 v[196:199], v239 offset:23552
	global_load_lds_dwordx4 v[194:195], off
	v_lshl_add_u64 v[216:217], s[4:5], 0, v[182:183]
	s_mov_b32 m0, s90
	s_nop 0
	global_load_lds_dwordx4 v[216:217], off
	s_add_u32 s56, s86, s36
	s_addc_u32 s57, s87, s37
	s_add_i32 s8, s8, s88
	v_lshl_add_u64 v[222:223], s[56:57], 0, v[180:181]
	s_mov_b32 m0, s8
	v_lshl_add_u64 v[224:225], s[56:57], 0, v[184:185]
	global_load_lds_dwordx4 v[222:223], off
	s_add_i32 m0, s8, 0x2000
	s_nop 0
	global_load_lds_dwordx4 v[224:225], off
	s_waitcnt vmcnt(8)
	s_waitcnt lgkmcnt(0)
	v_mfma_f32_16x16x32_bf16 v[62:65], v[132:135], v[148:151], v[62:65]
	v_mfma_f32_16x16x32_bf16 v[58:61], v[140:143], v[148:151], v[58:61]
	v_mfma_f32_16x16x32_bf16 v[46:49], v[132:135], v[156:159], v[46:49]
	v_mfma_f32_16x16x32_bf16 v[42:45], v[140:143], v[156:159], v[42:45]
	v_mfma_f32_16x16x32_bf16 v[30:33], v[132:135], v[164:167], v[30:33]
	v_mfma_f32_16x16x32_bf16 v[26:29], v[140:143], v[164:167], v[26:29]
	v_mfma_f32_16x16x32_bf16 v[14:17], v[132:135], v[172:175], v[14:17]
	v_mfma_f32_16x16x32_bf16 v[10:13], v[140:143], v[172:175], v[10:13]
	s_barrier
; #define PG8_STAGE(bufoff, gbase, voff) do { _Pragma("unroll") for (int _i = 0; _i < 2; ++_i) \
;         __builtin_amdgcn_global_load_lds((const unsigned*)((const char*)(gbase) + (voff)[_i]), (LAS unsigned*)(lds + (bufoff) + ldsw + _i * 8192), 16, 0, 0); } while (0)
; #define PG8_LDA(dst, b, h) do { _Pragma("unroll") for (int m = 0; m < 4; ++m) _Pragma("unroll") for (int k = 0; k < 2; ++k) dst[m][k] = *(const LAS bf16x8*)(lds + PG8_SA(b, h) + aoff + m * 2048 + k * 1024); } while (0)
; #define PG8_LDB(dst, b, h) do { _Pragma("unroll") for (int n = 0; n < 2; ++n) _Pragma("unroll") for (int k = 0; k < 2; ++k) dst[n][k] = *(const LAS bf16x8*)(lds + PG8_SB(b, h) + boff + n * 2048 + k * 1024); } while (0)
; #define PG8_MMA(ai, bj, At, Bt) do { __builtin_amdgcn_s_setprio(1); _Pragma("unroll") for (int m = 0; m < 4; ++m) _Pragma("unroll") for (int n = 0; n < 2; ++n) _Pragma("unroll") for (int k = 0; k < 2; ++k) \
;         acc[ai][bj][m][n] = __builtin_amdgcn_mfma_f32_16x16x32_bf16(Bt[n][k], At[m][k], acc[ai][bj][m][n], 0, 0, 0); __builtin_amdgcn_s_setprio(0); } while (0)
; #define PG8_WAIT_V(n) asm volatile("s_waitcnt vmcnt(" #n ")" ::: "memory")
; #define PG8_WAIT_L(n) asm volatile("s_waitcnt lgkmcnt(" #n ")" ::: "memory")
; #define PG8_BAR __builtin_amdgcn_s_barrier()
; #define PG8_SCHED __builtin_amdgcn_sched_barrier(0)
; template <class Epi>
; __device__ __forceinline__ void gemm_phase(LAS unsigned char* lds, const Gemm g, const Sched& S, const Epi& E) {
;     ...
;             PG8_LDB(B0, 0, 0); PG8_SCHED; PG8_LDA(At, 0, 0); PG8_STAGE(PG8_SA(1, 1), a1 + hstepA, voffA);
;             PG8_WAIT_L(8); PG8_BAR; PG8_WAIT_L(0); PG8_MMA(0, 0, At, B0); PG8_BAR; PG8_SCHED;
;             PG8_LDB(B1, 0, 1); PG8_STAGE(PG8_SB(0, 0), b2, voffB);
;             PG8_BAR; PG8_WAIT_L(0); PG8_MMA(0, 1, At, B1); PG8_BAR;
;             PG8_LDA(At, 0, 1); PG8_STAGE(PG8_SA(0, 0), a2, voffA);
;             PG8_BAR; PG8_WAIT_L(0); PG8_MMA(1, 0, At, B0); PG8_BAR; PG8_SCHED;
;             PG8_STAGE(PG8_SB(0, 1), b2 + hstepB, voffB);
;             PG8_WAIT_V(6); PG8_BAR; PG8_MMA(1, 1, At, B1); PG8_BAR;
;             PG8_LDB(B0, 1, 0); PG8_SCHED; PG8_LDA(At, 1, 0); PG8_STAGE(PG8_SA(0, 1), a2 + hstepA, voffA);
;             PG8_WAIT_L(8); PG8_BAR; PG8_WAIT_L(0); PG8_MMA(0, 0, At, B0); PG8_BAR; PG8_SCHED;
	s_setprio 1
	v_mfma_f32_16x16x32_bf16 v[62:65], v[136:139], v[152:155], v[62:65]
	v_mfma_f32_16x16x32_bf16 v[58:61], v[144:147], v[152:155], v[58:61]
	v_mfma_f32_16x16x32_bf16 v[46:49], v[136:139], v[160:163], v[46:49]
	v_mfma_f32_16x16x32_bf16 v[42:45], v[144:147], v[160:163], v[42:45]
	v_mfma_f32_16x16x32_bf16 v[30:33], v[136:139], v[168:171], v[30:33]
	v_mfma_f32_16x16x32_bf16 v[26:29], v[144:147], v[168:171], v[26:29]
	v_mfma_f32_16x16x32_bf16 v[14:17], v[136:139], v[196:199], v[14:17]
	v_mfma_f32_16x16x32_bf16 v[10:13], v[144:147], v[196:199], v[10:13]
	v_mfma_f32_16x16x32_bf16 v[54:57], v[200:203], v[148:151], v[54:57]
	v_mfma_f32_16x16x32_bf16 v[50:53], v[208:211], v[148:151], v[50:53]
	v_mfma_f32_16x16x32_bf16 v[38:41], v[200:203], v[156:159], v[38:41]
	v_mfma_f32_16x16x32_bf16 v[34:37], v[208:211], v[156:159], v[34:37]
	v_mfma_f32_16x16x32_bf16 v[22:25], v[200:203], v[164:167], v[22:25]
	v_mfma_f32_16x16x32_bf16 v[18:21], v[208:211], v[164:167], v[18:21]
	v_mfma_f32_16x16x32_bf16 v[6:9], v[200:203], v[172:175], v[6:9]
	v_mfma_f32_16x16x32_bf16 v[2:5], v[208:211], v[172:175], v[2:5]
	v_mfma_f32_16x16x32_bf16 v[54:57], v[204:207], v[152:155], v[54:57]
	v_mfma_f32_16x16x32_bf16 v[50:53], v[212:215], v[152:155], v[50:53]
	v_mfma_f32_16x16x32_bf16 v[38:41], v[204:207], v[160:163], v[38:41]
	v_mfma_f32_16x16x32_bf16 v[34:37], v[212:215], v[160:163], v[34:37]
	v_mfma_f32_16x16x32_bf16 v[22:25], v[204:207], v[168:171], v[22:25]
	v_mfma_f32_16x16x32_bf16 v[18:21], v[212:215], v[168:171], v[18:21]
	v_mfma_f32_16x16x32_bf16 v[6:9], v[204:207], v[196:199], v[6:9]
	v_mfma_f32_16x16x32_bf16 v[2:5], v[212:215], v[196:199], v[2:5]
	s_setprio 0
	s_barrier
	s_add_i32 s8, 0, 0x18000
	v_add_u32_e32 v144, s8, v236
	ds_read_b128 v[132:135], v144
	ds_read_b128 v[136:139], v144 offset:1024
	ds_read_b128 v[140:143], v144 offset:2048
	ds_read_b128 v[144:147], v144 offset:3072
	s_add_u32 s4, s4, s6
	s_addc_u32 s5, s5, s7
	s_mov_b32 m0, s91
	v_lshl_add_u64 v[200:201], s[4:5], 0, v[178:179]
	ds_read_b128 v[148:151], v239 offset:32768
	ds_read_b128 v[152:155], v239 offset:33792
	ds_read_b128 v[156:159], v239 offset:34816
	ds_read_b128 v[160:163], v239 offset:35840
	ds_read_b128 v[164:167], v239 offset:36864
	ds_read_b128 v[168:171], v239 offset:37888
	ds_read_b128 v[172:175], v239 offset:38912
	ds_read_b128 v[196:199], v239 offset:39936
	global_load_lds_dwordx4 v[200:201], off
	v_lshl_add_u64 v[200:201], s[4:5], 0, v[182:183]
	s_mov_b32 m0, s92
	s_nop 0
	global_load_lds_dwordx4 v[200:201], off
	s_add_i32 s4, 0, 0x1c000
	v_add_u32_e32 v212, s4, v236
	ds_read_b128 v[200:203], v212
	ds_read_b128 v[204:207], v212 offset:1024
	ds_read_b128 v[208:211], v212 offset:2048
	ds_read_b128 v[212:215], v212 offset:3072
	s_waitcnt vmcnt(8)
	s_waitcnt lgkmcnt(0)
	v_mfma_f32_16x16x32_bf16 v[126:129], v[132:135], v[148:151], v[126:129]
	v_mfma_f32_16x16x32_bf16 v[122:125], v[140:143], v[148:151], v[122:125]
	v_mfma_f32_16x16x32_bf16 v[110:113], v[132:135], v[156:159], v[110:113]
	v_mfma_f32_16x16x32_bf16 v[106:109], v[140:143], v[156:159], v[106:109]
	v_mfma_f32_16x16x32_bf16 v[94:97], v[132:135], v[164:167], v[94:97]
	v_mfma_f32_16x16x32_bf16 v[90:93], v[140:143], v[164:167], v[90:93]
	v_mfma_f32_16x16x32_bf16 v[78:81], v[132:135], v[172:175], v[78:81]
	v_mfma_f32_16x16x32_bf16 v[74:77], v[140:143], v[172:175], v[74:77]
	s_barrier
	s_setprio 1
	v_mfma_f32_16x16x32_bf16 v[126:129], v[136:139], v[152:155], v[126:129]
	v_mfma_f32_16x16x32_bf16 v[122:125], v[144:147], v[152:155], v[122:125]
	v_mfma_f32_16x16x32_bf16 v[110:113], v[136:139], v[160:163], v[110:113]
	v_mfma_f32_16x16x32_bf16 v[106:109], v[144:147], v[160:163], v[106:109]
	v_mfma_f32_16x16x32_bf16 v[94:97], v[136:139], v[168:171], v[94:97]
	v_mfma_f32_16x16x32_bf16 v[90:93], v[144:147], v[168:171], v[90:93]
	v_mfma_f32_16x16x32_bf16 v[78:81], v[136:139], v[196:199], v[78:81]
	v_mfma_f32_16x16x32_bf16 v[74:77], v[144:147], v[196:199], v[74:77]
	v_mfma_f32_16x16x32_bf16 v[118:121], v[200:203], v[148:151], v[118:121]
	v_mfma_f32_16x16x32_bf16 v[114:117], v[208:211], v[148:151], v[114:117]
	v_mfma_f32_16x16x32_bf16 v[102:105], v[200:203], v[156:159], v[102:105]
	v_mfma_f32_16x16x32_bf16 v[98:101], v[208:211], v[156:159], v[98:101]
	v_mfma_f32_16x16x32_bf16 v[86:89], v[200:203], v[164:167], v[86:89]
	v_mfma_f32_16x16x32_bf16 v[82:85], v[208:211], v[164:167], v[82:85]
	v_mfma_f32_16x16x32_bf16 v[70:73], v[200:203], v[172:175], v[70:73]
	v_mfma_f32_16x16x32_bf16 v[66:69], v[208:211], v[172:175], v[66:69]
	v_mfma_f32_16x16x32_bf16 v[118:121], v[204:207], v[152:155], v[118:121]
	v_mfma_f32_16x16x32_bf16 v[114:117], v[212:215], v[152:155], v[114:117]
	v_mfma_f32_16x16x32_bf16 v[102:105], v[204:207], v[160:163], v[102:105]
	v_mfma_f32_16x16x32_bf16 v[98:101], v[212:215], v[160:163], v[98:101]
	v_mfma_f32_16x16x32_bf16 v[86:89], v[204:207], v[168:171], v[86:89]
	v_mfma_f32_16x16x32_bf16 v[82:85], v[212:215], v[168:171], v[82:85]
	v_mfma_f32_16x16x32_bf16 v[70:73], v[204:207], v[196:199], v[70:73]
	v_mfma_f32_16x16x32_bf16 v[66:69], v[212:215], v[196:199], v[66:69]
	s_setprio 0
	s_barrier
; #define PG8_STAGE(bufoff, gbase, voff) do { _Pragma("unroll") for (int _i = 0; _i < 2; ++_i) \
;         __builtin_amdgcn_global_load_lds((const unsigned*)((const char*)(gbase) + (voff)[_i]), (LAS unsigned*)(lds + (bufoff) + ldsw + _i * 8192), 16, 0, 0); } while (0)
; #define PG8_LDA(dst, b, h) do { _Pragma("unroll") for (int m = 0; m < 4; ++m) _Pragma("unroll") for (int k = 0; k < 2; ++k) dst[m][k] = *(const LAS bf16x8*)(lds + PG8_SA(b, h) + aoff + m * 2048 + k * 1024); } while (0)
; #define PG8_LDB(dst, b, h) do { _Pragma("unroll") for (int n = 0; n < 2; ++n) _Pragma("unroll") for (int k = 0; k < 2; ++k) dst[n][k] = *(const LAS bf16x8*)(lds + PG8_SB(b, h) + boff + n * 2048 + k * 1024); } while (0)
; #define PG8_MMA(ai, bj, At, Bt) do { __builtin_amdgcn_s_setprio(1); _Pragma("unroll") for (int m = 0; m < 4; ++m) _Pragma("unroll") for (int n = 0; n < 2; ++n) _Pragma("unroll") for (int k = 0; k < 2; ++k) \
;         acc[ai][bj][m][n] = __builtin_amdgcn_mfma_f32_16x16x32_bf16(Bt[n][k], At[m][k], acc[ai][bj][m][n], 0, 0, 0); __builtin_amdgcn_s_setprio(0); } while (0)
; #define PG8_WAIT_V(n) asm volatile("s_waitcnt vmcnt(" #n ")" ::: "memory")
; #define PG8_WAIT_L(n) asm volatile("s_waitcnt lgkmcnt(" #n ")" ::: "memory")
; #define PG8_BAR __builtin_amdgcn_s_barrier()
; #define PG8_SCHED __builtin_amdgcn_sched_barrier(0)
; template <class Epi>
; __device__ __forceinline__ void gemm_phase(LAS unsigned char* lds, const Gemm g, const Sched& S, const Epi& E) {
;     ...
;             PG8_LDB(B1, 1, 1); PG8_STAGE(PG8_SB(1, 0), b3, voffB);
;             PG8_BAR; PG8_WAIT_L(0); PG8_MMA(0, 1, At, B1); PG8_BAR;
;             PG8_LDA(At, 1, 1); PG8_STAGE(PG8_SA(1, 0), a3, voffA);
;             PG8_BAR; PG8_WAIT_L(0); PG8_MMA(1, 0, At, B0); PG8_BAR; PG8_SCHED;
;             PG8_STAGE(PG8_SB(1, 1), b3 + hstepB, voffB);
;             PG8_WAIT_V(6); PG8_BAR; PG8_MMA(1, 1, At, B1); PG8_BAR;
;         }
	s_add_i32 s5, s8, s88
	v_lshl_add_u64 v[176:177], v[176:177], 0, s[60:61]
	s_mov_b32 m0, s5
	s_nop 0
	global_load_lds_dwordx4 v[176:177], off
	v_lshl_add_u64 v[176:177], v[192:193], 0, s[60:61]
	s_add_i32 m0, s5, 0x2000
	s_nop 0
	global_load_lds_dwordx4 v[176:177], off
	s_mov_b32 m0, s93
	v_lshl_add_u64 v[176:177], v[194:195], 0, s[60:61]
	ds_read_b128 v[148:151], v239 offset:49152
	ds_read_b128 v[152:155], v239 offset:50176
	ds_read_b128 v[156:159], v239 offset:51200
	ds_read_b128 v[160:163], v239 offset:52224
	ds_read_b128 v[164:167], v239 offset:53248
	ds_read_b128 v[168:171], v239 offset:54272
	ds_read_b128 v[172:175], v239 offset:55296
	ds_read_b128 v[196:199], v239 offset:56320
	global_load_lds_dwordx4 v[176:177], off
	v_lshl_add_u64 v[176:177], v[216:217], 0, s[60:61]
	s_mov_b32 m0, s94
	s_nop 0
	global_load_lds_dwordx4 v[176:177], off
	s_add_i32 s4, s4, s88
	v_lshl_add_u64 v[176:177], v[222:223], 0, s[60:61]
	s_mov_b32 m0, s4
	s_nop 0
	global_load_lds_dwordx4 v[176:177], off
	v_lshl_add_u64 v[176:177], v[224:225], 0, s[60:61]
	s_add_i32 m0, s4, 0x2000
	s_nop 0
	global_load_lds_dwordx4 v[176:177], off
	s_waitcnt vmcnt(8)
	s_waitcnt lgkmcnt(0)
	v_mfma_f32_16x16x32_bf16 v[62:65], v[132:135], v[148:151], v[62:65]
	v_mfma_f32_16x16x32_bf16 v[58:61], v[140:143], v[148:151], v[58:61]
	v_mfma_f32_16x16x32_bf16 v[46:49], v[132:135], v[156:159], v[46:49]
	v_mfma_f32_16x16x32_bf16 v[42:45], v[140:143], v[156:159], v[42:45]
	v_mfma_f32_16x16x32_bf16 v[30:33], v[132:135], v[164:167], v[30:33]
	v_mfma_f32_16x16x32_bf16 v[26:29], v[140:143], v[164:167], v[26:29]
	v_mfma_f32_16x16x32_bf16 v[14:17], v[132:135], v[172:175], v[14:17]
	v_mfma_f32_16x16x32_bf16 v[10:13], v[140:143], v[172:175], v[10:13]
	s_barrier
	s_setprio 1
	v_mfma_f32_16x16x32_bf16 v[62:65], v[136:139], v[152:155], v[62:65]
	v_mfma_f32_16x16x32_bf16 v[58:61], v[144:147], v[152:155], v[58:61]
	v_mfma_f32_16x16x32_bf16 v[46:49], v[136:139], v[160:163], v[46:49]
	v_mfma_f32_16x16x32_bf16 v[42:45], v[144:147], v[160:163], v[42:45]
	v_mfma_f32_16x16x32_bf16 v[30:33], v[136:139], v[168:171], v[30:33]
	v_mfma_f32_16x16x32_bf16 v[26:29], v[144:147], v[168:171], v[26:29]
	v_mfma_f32_16x16x32_bf16 v[14:17], v[136:139], v[196:199], v[14:17]
	v_mfma_f32_16x16x32_bf16 v[10:13], v[144:147], v[196:199], v[10:13]
	v_mfma_f32_16x16x32_bf16 v[54:57], v[200:203], v[148:151], v[54:57]
	v_mfma_f32_16x16x32_bf16 v[50:53], v[208:211], v[148:151], v[50:53]
	v_mfma_f32_16x16x32_bf16 v[38:41], v[200:203], v[156:159], v[38:41]
	v_mfma_f32_16x16x32_bf16 v[34:37], v[208:211], v[156:159], v[34:37]
	v_mfma_f32_16x16x32_bf16 v[22:25], v[200:203], v[164:167], v[22:25]
	v_mfma_f32_16x16x32_bf16 v[18:21], v[208:211], v[164:167], v[18:21]
	v_mfma_f32_16x16x32_bf16 v[6:9], v[200:203], v[172:175], v[6:9]
	v_mfma_f32_16x16x32_bf16 v[2:5], v[208:211], v[172:175], v[2:5]
	v_mfma_f32_16x16x32_bf16 v[54:57], v[204:207], v[152:155], v[54:57]
	v_mfma_f32_16x16x32_bf16 v[50:53], v[212:215], v[152:155], v[50:53]
	v_mfma_f32_16x16x32_bf16 v[38:41], v[204:207], v[160:163], v[38:41]
	v_mfma_f32_16x16x32_bf16 v[34:37], v[212:215], v[160:163], v[34:37]
	v_mfma_f32_16x16x32_bf16 v[22:25], v[204:207], v[168:171], v[22:25]
	v_mfma_f32_16x16x32_bf16 v[18:21], v[212:215], v[168:171], v[18:21]
	v_mfma_f32_16x16x32_bf16 v[6:9], v[204:207], v[196:199], v[6:9]
	v_mfma_f32_16x16x32_bf16 v[2:5], v[212:215], v[196:199], v[2:5]
	s_setprio 0
	s_add_u32 s0, s0, 0x100
	s_addc_u32 s1, s1, 0
	s_add_u32 s34, s34, 0x100
	s_addc_u32 s35, s35, 0
	s_cmp_ge_u32 s14, s73
	s_mov_b32 s4, s14
	s_barrier
	s_cbranch_scc0 .LBB0_649
	v_readfirstlane_b32 s98, v219
	s_nop 1
	s_bitcmp1_b32 s98, 8
	s_cbranch_scc1 .Lresync_x_649
	s_barrier

; #define PG8_STAGE(bufoff, gbase, voff) do { _Pragma("unroll") for (int _i = 0; _i < 2; ++_i) \
;         __builtin_amdgcn_global_load_lds((const unsigned*)((const char*)(gbase) + (voff)[_i]), (LAS unsigned*)(lds + (bufoff) + ldsw + _i * 8192), 16, 0, 0); } while (0)
; #define PG8_LDA(dst, b, h) do { _Pragma("unroll") for (int m = 0; m < 4; ++m) _Pragma("unroll") for (int k = 0; k < 2; ++k) dst[m][k] = *(const LAS bf16x8*)(lds + PG8_SA(b, h) + aoff + m * 2048 + k * 1024); } while (0)
; #define PG8_LDB(dst, b, h) do { _Pragma("unroll") for (int n = 0; n < 2; ++n) _Pragma("unroll") for (int k = 0; k < 2; ++k) dst[n][k] = *(const LAS bf16x8*)(lds + PG8_SB(b, h) + boff + n * 2048 + k * 1024); } while (0)
; #define PG8_MMA(ai, bj, At, Bt) do { __builtin_amdgcn_s_setprio(1); _Pragma("unroll") for (int m = 0; m < 4; ++m) _Pragma("unroll") for (int n = 0; n < 2; ++n) _Pragma("unroll") for (int k = 0; k < 2; ++k) \
;         acc[ai][bj][m][n] = __builtin_amdgcn_mfma_f32_16x16x32_bf16(Bt[n][k], At[m][k], acc[ai][bj][m][n], 0, 0, 0); __builtin_amdgcn_s_setprio(0); } while (0)
; #define PG8_WAIT_L(n) asm volatile("s_waitcnt lgkmcnt(" #n ")" ::: "memory")
; #define PG8_BAR __builtin_amdgcn_s_barrier()
; #define PG8_SCHED __builtin_amdgcn_sched_barrier(0)
; template <class Epi>
; __device__ __forceinline__ void gemm_phase(LAS unsigned char* lds, const Gemm g, const Sched& S, const Epi& E) {
;     ...
;         for (int t = 0; t < nt; t += 2) {
;             const bool last = (t == nt - 2);
;             const char* a1 = cA + (size_t)(t + 1) * kstep;
;             const char* a2 = last ? nA : cA + (size_t)(t + 2) * kstep; const char* b2 = last ? nB : cB + (size_t)(t + 2) * kstep;
;             const char* a3 = a2 + kstep; const char* b3 = b2 + kstep;
;             PG8_LDB(B0, 0, 0); PG8_SCHED; PG8_LDA(At, 0, 0); PG8_STAGE(PG8_SA(1, 1), a1 + hstepA, voffA);
;             PG8_WAIT_L(8); PG8_BAR; PG8_WAIT_L(0); PG8_MMA(0, 0, At, B0); PG8_BAR; PG8_SCHED;
;             PG8_LDB(B1, 0, 1); PG8_STAGE(PG8_SB(0, 0), b2, voffB);
;             PG8_BAR; PG8_WAIT_L(0); PG8_MMA(0, 1, At, B1); PG8_BAR;
;             PG8_LDA(At, 0, 1); PG8_STAGE(PG8_SA(0, 0), a2, voffA);
;             PG8_BAR; PG8_WAIT_L(0); PG8_MMA(1, 0, At, B0); PG8_BAR; PG8_SCHED;
.Lresync_y_825:
.LBB0_825:
	s_add_i32 s86, s68, 2
	s_add_u32 s70, s4, 0x80
	s_addc_u32 s69, s5, 0
	s_add_i32 s87, 0, 0x10000
	v_add_u32_e32 v144, s87, v145
	ds_read_b128 v[152:155], v144
	ds_read_b128 v[156:159], v144 offset:1024
	ds_read_b128 v[160:163], v144 offset:2048
	ds_read_b128 v[164:167], v144 offset:3072
	s_cmp_eq_u32 s77, s68
	s_cselect_b32 s68, s59, s70
	s_cselect_b32 s69, s57, s69
	s_cselect_b32 s71, s82, s85
	s_cselect_b32 s70, s83, s84
	v_lshl_add_u64 v[192:193], s[4:5], 0, v[136:137]
	s_add_i32 m0, s33, 0xc000
	ds_read_b128 v[168:171], v151
	ds_read_b128 v[172:175], v151 offset:1024
	ds_read_b128 v[176:179], v151 offset:2048
	ds_read_b128 v[180:183], v151 offset:3072
	ds_read_b128 v[184:187], v151 offset:4096
	ds_read_b128 v[188:191], v151 offset:5120
	ds_read_b128 v[196:199], v151 offset:6144
	ds_read_b128 v[200:203], v151 offset:7168
	global_load_lds_dwordx4 v[192:193], off
	v_lshl_add_u64 v[192:193], s[4:5], 0, v[138:139]
	s_add_i32 m0, s33, 0xe000
	s_nop 0
	global_load_lds_dwordx4 v[192:193], off
	s_add_i32 s88, 0, 0x14000
	v_add_u32_e32 v144, s88, v145
	ds_read_b128 v[204:207], v144
	ds_read_b128 v[208:211], v144 offset:1024
	ds_read_b128 v[212:215], v144 offset:2048
	ds_read_b128 v[234:237], v144 offset:3072
	s_waitcnt vmcnt(8)
	s_waitcnt lgkmcnt(0)
	v_mfma_f32_16x16x32_bf16 v[126:129], v[152:155], v[168:171], v[126:129]
	v_mfma_f32_16x16x32_bf16 v[122:125], v[160:163], v[168:171], v[122:125]
	v_mfma_f32_16x16x32_bf16 v[110:113], v[152:155], v[176:179], v[110:113]
	v_mfma_f32_16x16x32_bf16 v[106:109], v[160:163], v[176:179], v[106:109]
	v_mfma_f32_16x16x32_bf16 v[94:97], v[152:155], v[184:187], v[94:97]
	v_mfma_f32_16x16x32_bf16 v[90:93], v[160:163], v[184:187], v[90:93]
	v_mfma_f32_16x16x32_bf16 v[78:81], v[152:155], v[196:199], v[78:81]
	v_mfma_f32_16x16x32_bf16 v[74:77], v[160:163], v[196:199], v[74:77]
	s_barrier
	s_setprio 1
	v_mfma_f32_16x16x32_bf16 v[126:129], v[156:159], v[172:175], v[126:129]
	v_mfma_f32_16x16x32_bf16 v[122:125], v[164:167], v[172:175], v[122:125]
	v_mfma_f32_16x16x32_bf16 v[110:113], v[156:159], v[180:183], v[110:113]
	v_mfma_f32_16x16x32_bf16 v[106:109], v[164:167], v[180:183], v[106:109]
	v_mfma_f32_16x16x32_bf16 v[94:97], v[156:159], v[188:191], v[94:97]
	v_mfma_f32_16x16x32_bf16 v[90:93], v[164:167], v[188:191], v[90:93]
	v_mfma_f32_16x16x32_bf16 v[78:81], v[156:159], v[200:203], v[78:81]
	v_mfma_f32_16x16x32_bf16 v[74:77], v[164:167], v[200:203], v[74:77]
	v_mfma_f32_16x16x32_bf16 v[118:121], v[204:207], v[168:171], v[118:121]
	v_mfma_f32_16x16x32_bf16 v[114:117], v[212:215], v[168:171], v[114:117]
	v_mfma_f32_16x16x32_bf16 v[102:105], v[204:207], v[176:179], v[102:105]
	v_mfma_f32_16x16x32_bf16 v[98:101], v[212:215], v[176:179], v[98:101]
	v_mfma_f32_16x16x32_bf16 v[86:89], v[204:207], v[184:187], v[86:89]
	v_mfma_f32_16x16x32_bf16 v[82:85], v[212:215], v[184:187], v[82:85]
	v_mfma_f32_16x16x32_bf16 v[70:73], v[204:207], v[196:199], v[70:73]
	v_mfma_f32_16x16x32_bf16 v[66:69], v[212:215], v[196:199], v[66:69]
	v_mfma_f32_16x16x32_bf16 v[118:121], v[208:211], v[172:175], v[118:121]
	v_mfma_f32_16x16x32_bf16 v[114:117], v[234:237], v[172:175], v[114:117]
	v_mfma_f32_16x16x32_bf16 v[102:105], v[208:211], v[180:183], v[102:105]
	v_mfma_f32_16x16x32_bf16 v[98:101], v[234:237], v[180:183], v[98:101]
	v_mfma_f32_16x16x32_bf16 v[86:89], v[208:211], v[188:191], v[86:89]
	v_mfma_f32_16x16x32_bf16 v[82:85], v[234:237], v[188:191], v[82:85]
	v_mfma_f32_16x16x32_bf16 v[70:73], v[208:211], v[200:203], v[70:73]
	v_mfma_f32_16x16x32_bf16 v[66:69], v[234:237], v[200:203], v[66:69]
	s_setprio 0
	s_barrier
	s_add_i32 s87, s87, s51
	v_lshl_add_u64 v[192:193], s[70:71], 0, v[0:1]
	s_mov_b32 m0, s87
	s_nop 0
	global_load_lds_dwordx4 v[192:193], off
	v_lshl_add_u64 v[216:217], s[70:71], 0, v[134:135]
	s_add_i32 m0, s87, 0x2000
	s_nop 0
	global_load_lds_dwordx4 v[216:217], off
	s_mov_b32 m0, s33
	v_lshl_add_u64 v[222:223], s[68:69], 0, v[130:131]
	ds_read_b128 v[168:171], v151 offset:16384
	ds_read_b128 v[172:175], v151 offset:17408
	ds_read_b128 v[176:179], v151 offset:18432
	ds_read_b128 v[180:183], v151 offset:19456
	ds_read_b128 v[184:187], v151 offset:20480
	ds_read_b128 v[188:191], v151 offset:21504
	ds_read_b128 v[196:199], v151 offset:22528
	ds_read_b128 v[200:203], v151 offset:23552
	global_load_lds_dwordx4 v[222:223], off
	v_lshl_add_u64 v[224:225], s[68:69], 0, v[132:133]
	s_mov_b32 m0, s48
	s_nop 0
	global_load_lds_dwordx4 v[224:225], off
	s_add_u32 s70, s70, s14
	s_addc_u32 s71, s71, s15
	s_add_i32 s87, s88, s51
	v_lshl_add_u64 v[226:227], s[70:71], 0, v[0:1]
	s_mov_b32 m0, s87
	v_lshl_add_u64 v[228:229], s[70:71], 0, v[134:135]
	global_load_lds_dwordx4 v[226:227], off
	s_add_i32 m0, s87, 0x2000
	s_nop 0
	global_load_lds_dwordx4 v[228:229], off
	s_waitcnt vmcnt(8)
	s_waitcnt lgkmcnt(0)
	v_mfma_f32_16x16x32_bf16 v[62:65], v[152:155], v[168:171], v[62:65]
	v_mfma_f32_16x16x32_bf16 v[58:61], v[160:163], v[168:171], v[58:61]
	v_mfma_f32_16x16x32_bf16 v[46:49], v[152:155], v[176:179], v[46:49]
	v_mfma_f32_16x16x32_bf16 v[42:45], v[160:163], v[176:179], v[42:45]
	v_mfma_f32_16x16x32_bf16 v[30:33], v[152:155], v[184:187], v[30:33]
	v_mfma_f32_16x16x32_bf16 v[26:29], v[160:163], v[184:187], v[26:29]
	v_mfma_f32_16x16x32_bf16 v[14:17], v[152:155], v[196:199], v[14:17]
	v_mfma_f32_16x16x32_bf16 v[10:13], v[160:163], v[196:199], v[10:13]
	s_barrier
; #define PG8_STAGE(bufoff, gbase, voff) do { _Pragma("unroll") for (int _i = 0; _i < 2; ++_i) \
;         __builtin_amdgcn_global_load_lds((const unsigned*)((const char*)(gbase) + (voff)[_i]), (LAS unsigned*)(lds + (bufoff) + ldsw + _i * 8192), 16, 0, 0); } while (0)
; #define PG8_LDA(dst, b, h) do { _Pragma("unroll") for (int m = 0; m < 4; ++m) _Pragma("unroll") for (int k = 0; k < 2; ++k) dst[m][k] = *(const LAS bf16x8*)(lds + PG8_SA(b, h) + aoff + m * 2048 + k * 1024); } while (0)
; #define PG8_LDB(dst, b, h) do { _Pragma("unroll") for (int n = 0; n < 2; ++n) _Pragma("unroll") for (int k = 0; k < 2; ++k) dst[n][k] = *(const LAS bf16x8*)(lds + PG8_SB(b, h) + boff + n * 2048 + k * 1024); } while (0)
; #define PG8_MMA(ai, bj, At, Bt) do { __builtin_amdgcn_s_setprio(1); _Pragma("unroll") for (int m = 0; m < 4; ++m) _Pragma("unroll") for (int n = 0; n < 2; ++n) _Pragma("unroll") for (int k = 0; k < 2; ++k) \
;         acc[ai][bj][m][n] = __builtin_amdgcn_mfma_f32_16x16x32_bf16(Bt[n][k], At[m][k], acc[ai][bj][m][n], 0, 0, 0); __builtin_amdgcn_s_setprio(0); } while (0)
; #define PG8_WAIT_V(n) asm volatile("s_waitcnt vmcnt(" #n ")" ::: "memory")
; #define PG8_WAIT_L(n) asm volatile("s_waitcnt lgkmcnt(" #n ")" ::: "memory")
; #define PG8_BAR __builtin_amdgcn_s_barrier()
; #define PG8_SCHED __builtin_amdgcn_sched_barrier(0)
; template <class Epi>
; __device__ __forceinline__ void gemm_phase(LAS unsigned char* lds, const Gemm g, const Sched& S, const Epi& E) {
;     ...
;             PG8_BAR; PG8_WAIT_L(0); PG8_MMA(1, 0, At, B0); PG8_BAR; PG8_SCHED;
;             PG8_STAGE(PG8_SB(0, 1), b2 + hstepB, voffB);
;             PG8_WAIT_V(6); PG8_BAR; PG8_MMA(1, 1, At, B1); PG8_BAR;
;             PG8_LDB(B0, 1, 0); PG8_SCHED; PG8_LDA(At, 1, 0); PG8_STAGE(PG8_SA(0, 1), a2 + hstepA, voffA);
;             PG8_WAIT_L(8); PG8_BAR; PG8_WAIT_L(0); PG8_MMA(0, 0, At, B0); PG8_BAR; PG8_SCHED;
;             PG8_LDB(B1, 1, 1); PG8_STAGE(PG8_SB(1, 0), b3, voffB);
;             PG8_BAR; PG8_WAIT_L(0); PG8_MMA(0, 1, At, B1); PG8_BAR;
;             PG8_LDA(At, 1, 1); PG8_STAGE(PG8_SA(1, 0), a3, voffA);
;             PG8_BAR; PG8_WAIT_L(0); PG8_MMA(1, 0, At, B0); PG8_BAR; PG8_SCHED;
	s_setprio 1
	v_mfma_f32_16x16x32_bf16 v[62:65], v[156:159], v[172:175], v[62:65]
	v_mfma_f32_16x16x32_bf16 v[58:61], v[164:167], v[172:175], v[58:61]
	v_mfma_f32_16x16x32_bf16 v[46:49], v[156:159], v[180:183], v[46:49]
	v_mfma_f32_16x16x32_bf16 v[42:45], v[164:167], v[180:183], v[42:45]
	v_mfma_f32_16x16x32_bf16 v[30:33], v[156:159], v[188:191], v[30:33]
	v_mfma_f32_16x16x32_bf16 v[26:29], v[164:167], v[188:191], v[26:29]
	v_mfma_f32_16x16x32_bf16 v[14:17], v[156:159], v[200:203], v[14:17]
	v_mfma_f32_16x16x32_bf16 v[10:13], v[164:167], v[200:203], v[10:13]
	v_mfma_f32_16x16x32_bf16 v[54:57], v[204:207], v[168:171], v[54:57]
	v_mfma_f32_16x16x32_bf16 v[50:53], v[212:215], v[168:171], v[50:53]
	v_mfma_f32_16x16x32_bf16 v[38:41], v[204:207], v[176:179], v[38:41]
	v_mfma_f32_16x16x32_bf16 v[34:37], v[212:215], v[176:179], v[34:37]
	v_mfma_f32_16x16x32_bf16 v[22:25], v[204:207], v[184:187], v[22:25]
	v_mfma_f32_16x16x32_bf16 v[18:21], v[212:215], v[184:187], v[18:21]
	v_mfma_f32_16x16x32_bf16 v[6:9], v[204:207], v[196:199], v[6:9]
	v_mfma_f32_16x16x32_bf16 v[2:5], v[212:215], v[196:199], v[2:5]
	v_mfma_f32_16x16x32_bf16 v[54:57], v[208:211], v[172:175], v[54:57]
	v_mfma_f32_16x16x32_bf16 v[50:53], v[234:237], v[172:175], v[50:53]
	v_mfma_f32_16x16x32_bf16 v[38:41], v[208:211], v[180:183], v[38:41]
	v_mfma_f32_16x16x32_bf16 v[34:37], v[234:237], v[180:183], v[34:37]
	v_mfma_f32_16x16x32_bf16 v[22:25], v[208:211], v[188:191], v[22:25]
	v_mfma_f32_16x16x32_bf16 v[18:21], v[234:237], v[188:191], v[18:21]
	v_mfma_f32_16x16x32_bf16 v[6:9], v[208:211], v[200:203], v[6:9]
	v_mfma_f32_16x16x32_bf16 v[2:5], v[234:237], v[200:203], v[2:5]
	s_setprio 0
	s_barrier
	s_add_i32 s70, 0, 0x18000
	v_add_u32_e32 v144, s70, v145
	ds_read_b128 v[152:155], v144
	ds_read_b128 v[156:159], v144 offset:1024
	ds_read_b128 v[160:163], v144 offset:2048
	ds_read_b128 v[164:167], v144 offset:3072
	s_add_u32 s68, s68, s6
	s_addc_u32 s69, s69, s7
	s_mov_b32 m0, s58
	v_lshl_add_u64 v[204:205], s[68:69], 0, v[130:131]
	ds_read_b128 v[168:171], v151 offset:32768
	ds_read_b128 v[172:175], v151 offset:33792
	ds_read_b128 v[176:179], v151 offset:34816
	ds_read_b128 v[180:183], v151 offset:35840
	ds_read_b128 v[184:187], v151 offset:36864
	ds_read_b128 v[188:191], v151 offset:37888
	ds_read_b128 v[196:199], v151 offset:38912
	ds_read_b128 v[200:203], v151 offset:39936
	global_load_lds_dwordx4 v[204:205], off
	v_lshl_add_u64 v[204:205], s[68:69], 0, v[132:133]
	s_mov_b32 m0, s72
	s_nop 0
	global_load_lds_dwordx4 v[204:205], off
	s_add_i32 s68, 0, 0x1c000
	v_add_u32_e32 v144, s68, v145
	ds_read_b128 v[204:207], v144
	ds_read_b128 v[208:211], v144 offset:1024
	ds_read_b128 v[212:215], v144 offset:2048
	ds_read_b128 v[234:237], v144 offset:3072
	s_waitcnt vmcnt(8)
	s_waitcnt lgkmcnt(0)
	v_mfma_f32_16x16x32_bf16 v[126:129], v[152:155], v[168:171], v[126:129]
	v_mfma_f32_16x16x32_bf16 v[122:125], v[160:163], v[168:171], v[122:125]
	v_mfma_f32_16x16x32_bf16 v[110:113], v[152:155], v[176:179], v[110:113]
	v_mfma_f32_16x16x32_bf16 v[106:109], v[160:163], v[176:179], v[106:109]
	v_mfma_f32_16x16x32_bf16 v[94:97], v[152:155], v[184:187], v[94:97]
	v_mfma_f32_16x16x32_bf16 v[90:93], v[160:163], v[184:187], v[90:93]
	v_mfma_f32_16x16x32_bf16 v[78:81], v[152:155], v[196:199], v[78:81]
	v_mfma_f32_16x16x32_bf16 v[74:77], v[160:163], v[196:199], v[74:77]
	s_barrier
	s_setprio 1
	v_mfma_f32_16x16x32_bf16 v[126:129], v[156:159], v[172:175], v[126:129]
	v_mfma_f32_16x16x32_bf16 v[122:125], v[164:167], v[172:175], v[122:125]
	v_mfma_f32_16x16x32_bf16 v[110:113], v[156:159], v[180:183], v[110:113]
	v_mfma_f32_16x16x32_bf16 v[106:109], v[164:167], v[180:183], v[106:109]
	v_mfma_f32_16x16x32_bf16 v[94:97], v[156:159], v[188:191], v[94:97]
	v_mfma_f32_16x16x32_bf16 v[90:93], v[164:167], v[188:191], v[90:93]
	v_mfma_f32_16x16x32_bf16 v[78:81], v[156:159], v[200:203], v[78:81]
	v_mfma_f32_16x16x32_bf16 v[74:77], v[164:167], v[200:203], v[74:77]
	v_mfma_f32_16x16x32_bf16 v[118:121], v[204:207], v[168:171], v[118:121]
	v_mfma_f32_16x16x32_bf16 v[114:117], v[212:215], v[168:171], v[114:117]
	v_mfma_f32_16x16x32_bf16 v[102:105], v[204:207], v[176:179], v[102:105]
	v_mfma_f32_16x16x32_bf16 v[98:101], v[212:215], v[176:179], v[98:101]
	v_mfma_f32_16x16x32_bf16 v[86:89], v[204:207], v[184:187], v[86:89]
	v_mfma_f32_16x16x32_bf16 v[82:85], v[212:215], v[184:187], v[82:85]
	v_mfma_f32_16x16x32_bf16 v[70:73], v[204:207], v[196:199], v[70:73]
	v_mfma_f32_16x16x32_bf16 v[66:69], v[212:215], v[196:199], v[66:69]
	v_mfma_f32_16x16x32_bf16 v[118:121], v[208:211], v[172:175], v[118:121]
	v_mfma_f32_16x16x32_bf16 v[114:117], v[234:237], v[172:175], v[114:117]
	v_mfma_f32_16x16x32_bf16 v[102:105], v[208:211], v[180:183], v[102:105]
	v_mfma_f32_16x16x32_bf16 v[98:101], v[234:237], v[180:183], v[98:101]
	v_mfma_f32_16x16x32_bf16 v[86:89], v[208:211], v[188:191], v[86:89]
	v_mfma_f32_16x16x32_bf16 v[82:85], v[234:237], v[188:191], v[82:85]
	v_mfma_f32_16x16x32_bf16 v[70:73], v[208:211], v[200:203], v[70:73]
	v_mfma_f32_16x16x32_bf16 v[66:69], v[234:237], v[200:203], v[66:69]
	s_setprio 0
	s_barrier
; #define PG8_STAGE(bufoff, gbase, voff) do { _Pragma("unroll") for (int _i = 0; _i < 2; ++_i) \
;         __builtin_amdgcn_global_load_lds((const unsigned*)((const char*)(gbase) + (voff)[_i]), (LAS unsigned*)(lds + (bufoff) + ldsw + _i * 8192), 16, 0, 0); } while (0)
; #define PG8_LDA(dst, b, h) do { _Pragma("unroll") for (int m = 0; m < 4; ++m) _Pragma("unroll") for (int k = 0; k < 2; ++k) dst[m][k] = *(const LAS bf16x8*)(lds + PG8_SA(b, h) + aoff + m * 2048 + k * 1024); } while (0)
; #define PG8_MMA(ai, bj, At, Bt) do { __builtin_amdgcn_s_setprio(1); _Pragma("unroll") for (int m = 0; m < 4; ++m) _Pragma("unroll") for (int n = 0; n < 2; ++n) _Pragma("unroll") for (int k = 0; k < 2; ++k) \
;         acc[ai][bj][m][n] = __builtin_amdgcn_mfma_f32_16x16x32_bf16(Bt[n][k], At[m][k], acc[ai][bj][m][n], 0, 0, 0); __builtin_amdgcn_s_setprio(0); } while (0)
; #define PG8_WAIT_V(n) asm volatile("s_waitcnt vmcnt(" #n ")" ::: "memory")
; #define PG8_WAIT_L(n) asm volatile("s_waitcnt lgkmcnt(" #n ")" ::: "memory")
; #define PG8_BAR __builtin_amdgcn_s_barrier()
; #define PG8_SCHED __builtin_amdgcn_sched_barrier(0)
; template <class Epi>
; __device__ __forceinline__ void gemm_phase(LAS unsigned char* lds, const Gemm g, const Sched& S, const Epi& E) {
;     ...
;             PG8_LDA(At, 1, 1); PG8_STAGE(PG8_SA(1, 0), a3, voffA);
;             PG8_BAR; PG8_WAIT_L(0); PG8_MMA(1, 0, At, B0); PG8_BAR; PG8_SCHED;
;             PG8_STAGE(PG8_SB(1, 1), b3 + hstepB, voffB);
;             PG8_WAIT_V(6); PG8_BAR; PG8_MMA(1, 1, At, B1); PG8_BAR;
;         }
	s_add_i32 s69, s70, s51
	v_lshl_add_u64 v[192:193], v[192:193], 0, s[60:61]
	s_mov_b32 m0, s69
	s_nop 0
	global_load_lds_dwordx4 v[192:193], off
	v_lshl_add_u64 v[192:193], v[216:217], 0, s[60:61]
	s_add_i32 m0, s69, 0x2000
	s_nop 0
	global_load_lds_dwordx4 v[192:193], off
	s_mov_b32 m0, s75
	v_lshl_add_u64 v[192:193], v[222:223], 0, s[60:61]
	ds_read_b128 v[168:171], v151 offset:49152
	ds_read_b128 v[172:175], v151 offset:50176
	ds_read_b128 v[176:179], v151 offset:51200
	ds_read_b128 v[180:183], v151 offset:52224
	ds_read_b128 v[184:187], v151 offset:53248
	ds_read_b128 v[188:191], v151 offset:54272
	ds_read_b128 v[196:199], v151 offset:55296
	ds_read_b128 v[200:203], v151 offset:56320
	global_load_lds_dwordx4 v[192:193], off
	v_lshl_add_u64 v[192:193], v[224:225], 0, s[60:61]
	s_mov_b32 m0, s76
	s_nop 0
	global_load_lds_dwordx4 v[192:193], off
	s_add_i32 s68, s68, s51
	v_lshl_add_u64 v[192:193], v[226:227], 0, s[60:61]
	s_mov_b32 m0, s68
	s_nop 0
	global_load_lds_dwordx4 v[192:193], off
	v_lshl_add_u64 v[192:193], v[228:229], 0, s[60:61]
	s_add_i32 m0, s68, 0x2000
	s_nop 0
	global_load_lds_dwordx4 v[192:193], off
	s_waitcnt vmcnt(8)
	s_waitcnt lgkmcnt(0)
	v_mfma_f32_16x16x32_bf16 v[62:65], v[152:155], v[168:171], v[62:65]
	v_mfma_f32_16x16x32_bf16 v[58:61], v[160:163], v[168:171], v[58:61]
	v_mfma_f32_16x16x32_bf16 v[46:49], v[152:155], v[176:179], v[46:49]
	v_mfma_f32_16x16x32_bf16 v[42:45], v[160:163], v[176:179], v[42:45]
	v_mfma_f32_16x16x32_bf16 v[30:33], v[152:155], v[184:187], v[30:33]
	v_mfma_f32_16x16x32_bf16 v[26:29], v[160:163], v[184:187], v[26:29]
	v_mfma_f32_16x16x32_bf16 v[14:17], v[152:155], v[196:199], v[14:17]
	v_mfma_f32_16x16x32_bf16 v[10:13], v[160:163], v[196:199], v[10:13]
	s_barrier
	s_setprio 1
	v_mfma_f32_16x16x32_bf16 v[62:65], v[156:159], v[172:175], v[62:65]
	v_mfma_f32_16x16x32_bf16 v[58:61], v[164:167], v[172:175], v[58:61]
	v_mfma_f32_16x16x32_bf16 v[46:49], v[156:159], v[180:183], v[46:49]
	v_mfma_f32_16x16x32_bf16 v[42:45], v[164:167], v[180:183], v[42:45]
	v_mfma_f32_16x16x32_bf16 v[30:33], v[156:159], v[188:191], v[30:33]
	v_mfma_f32_16x16x32_bf16 v[26:29], v[164:167], v[188:191], v[26:29]
	v_mfma_f32_16x16x32_bf16 v[14:17], v[156:159], v[200:203], v[14:17]
	v_mfma_f32_16x16x32_bf16 v[10:13], v[164:167], v[200:203], v[10:13]
	v_mfma_f32_16x16x32_bf16 v[54:57], v[204:207], v[168:171], v[54:57]
	v_mfma_f32_16x16x32_bf16 v[50:53], v[212:215], v[168:171], v[50:53]
	v_mfma_f32_16x16x32_bf16 v[38:41], v[204:207], v[176:179], v[38:41]
	v_mfma_f32_16x16x32_bf16 v[34:37], v[212:215], v[176:179], v[34:37]
	v_mfma_f32_16x16x32_bf16 v[22:25], v[204:207], v[184:187], v[22:25]
	v_mfma_f32_16x16x32_bf16 v[18:21], v[212:215], v[184:187], v[18:21]
	v_mfma_f32_16x16x32_bf16 v[6:9], v[204:207], v[196:199], v[6:9]
	v_mfma_f32_16x16x32_bf16 v[2:5], v[212:215], v[196:199], v[2:5]
	v_mfma_f32_16x16x32_bf16 v[54:57], v[208:211], v[172:175], v[54:57]
	v_mfma_f32_16x16x32_bf16 v[50:53], v[234:237], v[172:175], v[50:53]
	v_mfma_f32_16x16x32_bf16 v[38:41], v[208:211], v[180:183], v[38:41]
	v_mfma_f32_16x16x32_bf16 v[34:37], v[234:237], v[180:183], v[34:37]
	v_mfma_f32_16x16x32_bf16 v[22:25], v[208:211], v[188:191], v[22:25]
	v_mfma_f32_16x16x32_bf16 v[18:21], v[234:237], v[188:191], v[18:21]
	v_mfma_f32_16x16x32_bf16 v[6:9], v[208:211], v[200:203], v[6:9]
	v_mfma_f32_16x16x32_bf16 v[2:5], v[234:237], v[200:203], v[2:5]
	s_setprio 0
	s_add_u32 s4, s4, 0x100
	s_addc_u32 s5, s5, 0
	s_add_u32 s84, s84, 0x100
	s_addc_u32 s85, s85, 0
	s_cmp_ge_u32 s86, s73
	s_mov_b32 s68, s86
	s_barrier
	s_cbranch_scc0 .LBB0_825
	v_readfirstlane_b32 s98, v219
	s_nop 1
	s_bitcmp1_b32 s98, 8
	s_cbranch_scc1 .Lresync_x_825
	s_barrier
